# Epilogue de-serialisation: on v15, the 10 fp16 in-place residual-add GEMM epilogues (EpiResid) rewritten so 8 residual loads are in flight and one counted vmcnt per 8-column chunk replaces the load-wa
# speedup vs baseline: 1.0218x; 1.0218x over previous
.LBB0_998:
	v_lshl_add_u32 v146, s76, 8, v1
	v_lshl_or_b32 v148, s73, 8, v163
	v_ashrrev_i32_e32 v147, 31, v146
	v_ashrrev_i32_e32 v149, 31, v148
	v_lshlrev_b64 v[150:151], 12, v[146:147]
	v_lshl_add_u64 v[150:151], s[64:65], 0, v[150:151]
	v_lshlrev_b64 v[148:149], 1, v[148:149]
	v_lshl_add_u64 v[150:151], v[150:151], 0, v[148:149]
	v_mov_b32_e32 v245, 0
	v_mov_b32_e32 v244, 0x10000
	v_lshl_add_u64 v[230:231], v[244:245], 0, v[150:151]
	v_mov_b32_e32 v244, 0x20000
	v_lshl_add_u64 v[232:233], v[244:245], 0, v[150:151]
	v_mov_b32_e32 v244, 0x30000
	v_lshl_add_u64 v[234:235], v[244:245], 0, v[150:151]
	v_mov_b32_e32 v244, 0x80000
	v_lshl_add_u64 v[236:237], v[244:245], 0, v[150:151]
	v_mov_b32_e32 v244, 0x90000
	v_lshl_add_u64 v[238:239], v[244:245], 0, v[150:151]
	v_mov_b32_e32 v244, 0xa0000
	v_lshl_add_u64 v[240:241], v[244:245], 0, v[150:151]
	v_mov_b32_e32 v244, 0xb0000
	v_lshl_add_u64 v[242:243], v[244:245], 0, v[150:151]
	global_load_dwordx4 v[146:149], v[150:151], off
	global_load_dwordx4 v[152:155], v[150:151], off offset:256
	global_load_dwordx4 v[156:159], v[230:231], off
	global_load_dwordx4 v[168:171], v[230:231], off offset:256
	global_load_dwordx4 v[172:175], v[232:233], off
	global_load_dwordx4 v[176:179], v[232:233], off offset:256
	global_load_dwordx4 v[180:183], v[234:235], off
	global_load_dwordx4 v[184:187], v[234:235], off offset:256
	s_waitcnt vmcnt(7)
	v_cvt_f32_f16_e32 v160, v146
	v_cvt_f32_f16_sdwa v161, v146 dst_sel:DWORD dst_unused:UNUSED_PAD src0_sel:WORD_1
	v_cvt_f32_f16_e32 v188, v147
	v_cvt_f32_f16_sdwa v189, v147 dst_sel:DWORD dst_unused:UNUSED_PAD src0_sel:WORD_1
	v_cvt_f32_f16_e32 v190, v148
	v_cvt_f32_f16_sdwa v191, v148 dst_sel:DWORD dst_unused:UNUSED_PAD src0_sel:WORD_1
	v_cvt_f32_f16_e32 v228, v149
	v_cvt_f32_f16_sdwa v229, v149 dst_sel:DWORD dst_unused:UNUSED_PAD src0_sel:WORD_1
	global_load_dwordx4 v[146:149], v[236:237], off
	v_pk_add_f32 v[126:127], v[160:161], v[126:127]
	v_pk_add_f32 v[128:129], v[188:189], v[128:129]
	v_pk_add_f32 v[122:123], v[190:191], v[122:123]
	v_pk_add_f32 v[124:125], v[228:229], v[124:125]
	v_cvt_pk_f16_f32 v125, v124, v125
	v_cvt_pk_f16_f32 v124, v122, v123
	v_cvt_pk_f16_f32 v123, v128, v129
	v_cvt_pk_f16_f32 v122, v126, v127
	global_store_dwordx4 v[150:151], v[122:125], off
	s_waitcnt vmcnt(8)
	v_cvt_f32_f16_e32 v160, v152
	v_cvt_f32_f16_sdwa v161, v152 dst_sel:DWORD dst_unused:UNUSED_PAD src0_sel:WORD_1
	v_cvt_f32_f16_e32 v188, v153
	v_cvt_f32_f16_sdwa v189, v153 dst_sel:DWORD dst_unused:UNUSED_PAD src0_sel:WORD_1
	v_cvt_f32_f16_e32 v190, v154
	v_cvt_f32_f16_sdwa v191, v154 dst_sel:DWORD dst_unused:UNUSED_PAD src0_sel:WORD_1
	v_cvt_f32_f16_e32 v228, v155
	v_cvt_f32_f16_sdwa v229, v155 dst_sel:DWORD dst_unused:UNUSED_PAD src0_sel:WORD_1
	global_load_dwordx4 v[152:155], v[236:237], off offset:256
	v_pk_add_f32 v[118:119], v[160:161], v[118:119]
	v_pk_add_f32 v[120:121], v[188:189], v[120:121]
	v_pk_add_f32 v[114:115], v[190:191], v[114:115]
	v_pk_add_f32 v[116:117], v[228:229], v[116:117]
	v_cvt_pk_f16_f32 v117, v116, v117
	v_cvt_pk_f16_f32 v116, v114, v115
	v_cvt_pk_f16_f32 v115, v120, v121
	v_cvt_pk_f16_f32 v114, v118, v119
	global_store_dwordx4 v[150:151], v[114:117], off offset:256
	s_waitcnt vmcnt(9)
	v_cvt_f32_f16_e32 v160, v156
	v_cvt_f32_f16_sdwa v161, v156 dst_sel:DWORD dst_unused:UNUSED_PAD src0_sel:WORD_1
	v_cvt_f32_f16_e32 v188, v157
	v_cvt_f32_f16_sdwa v189, v157 dst_sel:DWORD dst_unused:UNUSED_PAD src0_sel:WORD_1
	v_cvt_f32_f16_e32 v190, v158
	v_cvt_f32_f16_sdwa v191, v158 dst_sel:DWORD dst_unused:UNUSED_PAD src0_sel:WORD_1
	v_cvt_f32_f16_e32 v228, v159
	v_cvt_f32_f16_sdwa v229, v159 dst_sel:DWORD dst_unused:UNUSED_PAD src0_sel:WORD_1
	global_load_dwordx4 v[156:159], v[238:239], off
	v_pk_add_f32 v[110:111], v[160:161], v[110:111]
	v_pk_add_f32 v[112:113], v[188:189], v[112:113]
	v_pk_add_f32 v[106:107], v[190:191], v[106:107]
	v_pk_add_f32 v[108:109], v[228:229], v[108:109]
	v_cvt_pk_f16_f32 v109, v108, v109
	v_cvt_pk_f16_f32 v108, v106, v107
	v_cvt_pk_f16_f32 v107, v112, v113
	v_cvt_pk_f16_f32 v106, v110, v111
	global_store_dwordx4 v[230:231], v[106:109], off
	s_waitcnt vmcnt(10)
	v_cvt_f32_f16_e32 v160, v168
	v_cvt_f32_f16_sdwa v161, v168 dst_sel:DWORD dst_unused:UNUSED_PAD src0_sel:WORD_1
	v_cvt_f32_f16_e32 v188, v169
	v_cvt_f32_f16_sdwa v189, v169 dst_sel:DWORD dst_unused:UNUSED_PAD src0_sel:WORD_1
	v_cvt_f32_f16_e32 v190, v170
	v_cvt_f32_f16_sdwa v191, v170 dst_sel:DWORD dst_unused:UNUSED_PAD src0_sel:WORD_1
	v_cvt_f32_f16_e32 v228, v171
	v_cvt_f32_f16_sdwa v229, v171 dst_sel:DWORD dst_unused:UNUSED_PAD src0_sel:WORD_1
	global_load_dwordx4 v[168:171], v[238:239], off offset:256
	v_pk_add_f32 v[102:103], v[160:161], v[102:103]
	v_pk_add_f32 v[104:105], v[188:189], v[104:105]
	v_pk_add_f32 v[98:99], v[190:191], v[98:99]
	v_pk_add_f32 v[100:101], v[228:229], v[100:101]
	v_cvt_pk_f16_f32 v101, v100, v101
	v_cvt_pk_f16_f32 v100, v98, v99
	v_cvt_pk_f16_f32 v99, v104, v105
	v_cvt_pk_f16_f32 v98, v102, v103
	global_store_dwordx4 v[230:231], v[98:101], off offset:256
	s_waitcnt vmcnt(11)
	v_cvt_f32_f16_e32 v160, v172
	v_cvt_f32_f16_sdwa v161, v172 dst_sel:DWORD dst_unused:UNUSED_PAD src0_sel:WORD_1
	v_cvt_f32_f16_e32 v188, v173
	v_cvt_f32_f16_sdwa v189, v173 dst_sel:DWORD dst_unused:UNUSED_PAD src0_sel:WORD_1
	v_cvt_f32_f16_e32 v190, v174
	v_cvt_f32_f16_sdwa v191, v174 dst_sel:DWORD dst_unused:UNUSED_PAD src0_sel:WORD_1
	v_cvt_f32_f16_e32 v228, v175
	v_cvt_f32_f16_sdwa v229, v175 dst_sel:DWORD dst_unused:UNUSED_PAD src0_sel:WORD_1
	global_load_dwordx4 v[172:175], v[240:241], off
	v_pk_add_f32 v[94:95], v[160:161], v[94:95]
	v_pk_add_f32 v[96:97], v[188:189], v[96:97]
	v_pk_add_f32 v[90:91], v[190:191], v[90:91]
	v_pk_add_f32 v[92:93], v[228:229], v[92:93]
	v_cvt_pk_f16_f32 v93, v92, v93
	v_cvt_pk_f16_f32 v92, v90, v91
	v_cvt_pk_f16_f32 v91, v96, v97
	v_cvt_pk_f16_f32 v90, v94, v95
	global_store_dwordx4 v[232:233], v[90:93], off
	s_waitcnt vmcnt(12)
	v_cvt_f32_f16_e32 v160, v176
	v_cvt_f32_f16_sdwa v161, v176 dst_sel:DWORD dst_unused:UNUSED_PAD src0_sel:WORD_1
	v_cvt_f32_f16_e32 v188, v177
	v_cvt_f32_f16_sdwa v189, v177 dst_sel:DWORD dst_unused:UNUSED_PAD src0_sel:WORD_1
	v_cvt_f32_f16_e32 v190, v178
	v_cvt_f32_f16_sdwa v191, v178 dst_sel:DWORD dst_unused:UNUSED_PAD src0_sel:WORD_1
	v_cvt_f32_f16_e32 v228, v179
	v_cvt_f32_f16_sdwa v229, v179 dst_sel:DWORD dst_unused:UNUSED_PAD src0_sel:WORD_1
	global_load_dwordx4 v[176:179], v[240:241], off offset:256
	v_pk_add_f32 v[86:87], v[160:161], v[86:87]
	v_pk_add_f32 v[88:89], v[188:189], v[88:89]
	v_pk_add_f32 v[82:83], v[190:191], v[82:83]
	v_pk_add_f32 v[84:85], v[228:229], v[84:85]
	v_cvt_pk_f16_f32 v85, v84, v85
	v_cvt_pk_f16_f32 v84, v82, v83
	v_cvt_pk_f16_f32 v83, v88, v89
	v_cvt_pk_f16_f32 v82, v86, v87
	global_store_dwordx4 v[232:233], v[82:85], off offset:256
	s_waitcnt vmcnt(13)
	v_cvt_f32_f16_e32 v160, v180
	v_cvt_f32_f16_sdwa v161, v180 dst_sel:DWORD dst_unused:UNUSED_PAD src0_sel:WORD_1
	v_cvt_f32_f16_e32 v188, v181
	v_cvt_f32_f16_sdwa v189, v181 dst_sel:DWORD dst_unused:UNUSED_PAD src0_sel:WORD_1
	v_cvt_f32_f16_e32 v190, v182
	v_cvt_f32_f16_sdwa v191, v182 dst_sel:DWORD dst_unused:UNUSED_PAD src0_sel:WORD_1
	v_cvt_f32_f16_e32 v228, v183
	v_cvt_f32_f16_sdwa v229, v183 dst_sel:DWORD dst_unused:UNUSED_PAD src0_sel:WORD_1
	global_load_dwordx4 v[180:183], v[242:243], off
	v_pk_add_f32 v[78:79], v[160:161], v[78:79]
	v_pk_add_f32 v[80:81], v[188:189], v[80:81]
	v_pk_add_f32 v[74:75], v[190:191], v[74:75]
	v_pk_add_f32 v[76:77], v[228:229], v[76:77]
	v_cvt_pk_f16_f32 v77, v76, v77
	v_cvt_pk_f16_f32 v76, v74, v75
	v_cvt_pk_f16_f32 v75, v80, v81
	v_cvt_pk_f16_f32 v74, v78, v79
	global_store_dwordx4 v[234:235], v[74:77], off
	s_waitcnt vmcnt(14)
	v_cvt_f32_f16_e32 v160, v184
	v_cvt_f32_f16_sdwa v161, v184 dst_sel:DWORD dst_unused:UNUSED_PAD src0_sel:WORD_1
	v_cvt_f32_f16_e32 v188, v185
	v_cvt_f32_f16_sdwa v189, v185 dst_sel:DWORD dst_unused:UNUSED_PAD src0_sel:WORD_1
	v_cvt_f32_f16_e32 v190, v186
	v_cvt_f32_f16_sdwa v191, v186 dst_sel:DWORD dst_unused:UNUSED_PAD src0_sel:WORD_1
	v_cvt_f32_f16_e32 v228, v187
	v_cvt_f32_f16_sdwa v229, v187 dst_sel:DWORD dst_unused:UNUSED_PAD src0_sel:WORD_1
	global_load_dwordx4 v[184:187], v[242:243], off offset:256
	v_pk_add_f32 v[70:71], v[160:161], v[70:71]
	v_pk_add_f32 v[72:73], v[188:189], v[72:73]
	v_pk_add_f32 v[66:67], v[190:191], v[66:67]
	v_pk_add_f32 v[68:69], v[228:229], v[68:69]
	v_cvt_pk_f16_f32 v69, v68, v69
	v_cvt_pk_f16_f32 v68, v66, v67
	v_cvt_pk_f16_f32 v67, v72, v73
	v_cvt_pk_f16_f32 v66, v70, v71
	global_store_dwordx4 v[234:235], v[66:69], off offset:256
	s_waitcnt vmcnt(15)
	v_cvt_f32_f16_e32 v160, v146
	v_cvt_f32_f16_sdwa v161, v146 dst_sel:DWORD dst_unused:UNUSED_PAD src0_sel:WORD_1
	v_cvt_f32_f16_e32 v188, v147
	v_cvt_f32_f16_sdwa v189, v147 dst_sel:DWORD dst_unused:UNUSED_PAD src0_sel:WORD_1
	v_cvt_f32_f16_e32 v190, v148
	v_cvt_f32_f16_sdwa v191, v148 dst_sel:DWORD dst_unused:UNUSED_PAD src0_sel:WORD_1
	v_cvt_f32_f16_e32 v228, v149
	v_cvt_f32_f16_sdwa v229, v149 dst_sel:DWORD dst_unused:UNUSED_PAD src0_sel:WORD_1
	v_pk_add_f32 v[62:63], v[160:161], v[62:63]
	v_pk_add_f32 v[64:65], v[188:189], v[64:65]
	v_pk_add_f32 v[58:59], v[190:191], v[58:59]
	v_pk_add_f32 v[60:61], v[228:229], v[60:61]
	v_cvt_pk_f16_f32 v61, v60, v61
	v_cvt_pk_f16_f32 v60, v58, v59
	v_cvt_pk_f16_f32 v59, v64, v65
	v_cvt_pk_f16_f32 v58, v62, v63
	global_store_dwordx4 v[236:237], v[58:61], off
	s_waitcnt vmcnt(14)
	v_cvt_f32_f16_e32 v160, v152
	v_cvt_f32_f16_sdwa v161, v152 dst_sel:DWORD dst_unused:UNUSED_PAD src0_sel:WORD_1
	v_cvt_f32_f16_e32 v188, v153
	v_cvt_f32_f16_sdwa v189, v153 dst_sel:DWORD dst_unused:UNUSED_PAD src0_sel:WORD_1
	v_cvt_f32_f16_e32 v190, v154
	v_cvt_f32_f16_sdwa v191, v154 dst_sel:DWORD dst_unused:UNUSED_PAD src0_sel:WORD_1
	v_cvt_f32_f16_e32 v228, v155
	v_cvt_f32_f16_sdwa v229, v155 dst_sel:DWORD dst_unused:UNUSED_PAD src0_sel:WORD_1
	v_pk_add_f32 v[54:55], v[160:161], v[54:55]
	v_pk_add_f32 v[56:57], v[188:189], v[56:57]
	v_pk_add_f32 v[50:51], v[190:191], v[50:51]
	v_pk_add_f32 v[52:53], v[228:229], v[52:53]
	v_cvt_pk_f16_f32 v53, v52, v53
	v_cvt_pk_f16_f32 v52, v50, v51
	v_cvt_pk_f16_f32 v51, v56, v57
	v_cvt_pk_f16_f32 v50, v54, v55
	global_store_dwordx4 v[236:237], v[50:53], off offset:256
	s_waitcnt vmcnt(13)
	v_cvt_f32_f16_e32 v160, v156
	v_cvt_f32_f16_sdwa v161, v156 dst_sel:DWORD dst_unused:UNUSED_PAD src0_sel:WORD_1
	v_cvt_f32_f16_e32 v188, v157
	v_cvt_f32_f16_sdwa v189, v157 dst_sel:DWORD dst_unused:UNUSED_PAD src0_sel:WORD_1
	v_cvt_f32_f16_e32 v190, v158
	v_cvt_f32_f16_sdwa v191, v158 dst_sel:DWORD dst_unused:UNUSED_PAD src0_sel:WORD_1
	v_cvt_f32_f16_e32 v228, v159
	v_cvt_f32_f16_sdwa v229, v159 dst_sel:DWORD dst_unused:UNUSED_PAD src0_sel:WORD_1
	v_pk_add_f32 v[46:47], v[160:161], v[46:47]
	v_pk_add_f32 v[48:49], v[188:189], v[48:49]
	v_pk_add_f32 v[42:43], v[190:191], v[42:43]
	v_pk_add_f32 v[44:45], v[228:229], v[44:45]
	v_cvt_pk_f16_f32 v45, v44, v45
	v_cvt_pk_f16_f32 v44, v42, v43
	v_cvt_pk_f16_f32 v43, v48, v49
	v_cvt_pk_f16_f32 v42, v46, v47
	global_store_dwordx4 v[238:239], v[42:45], off
	s_waitcnt vmcnt(12)
	v_cvt_f32_f16_e32 v160, v168
	v_cvt_f32_f16_sdwa v161, v168 dst_sel:DWORD dst_unused:UNUSED_PAD src0_sel:WORD_1
	v_cvt_f32_f16_e32 v188, v169
	v_cvt_f32_f16_sdwa v189, v169 dst_sel:DWORD dst_unused:UNUSED_PAD src0_sel:WORD_1
	v_cvt_f32_f16_e32 v190, v170
	v_cvt_f32_f16_sdwa v191, v170 dst_sel:DWORD dst_unused:UNUSED_PAD src0_sel:WORD_1
	v_cvt_f32_f16_e32 v228, v171
	v_cvt_f32_f16_sdwa v229, v171 dst_sel:DWORD dst_unused:UNUSED_PAD src0_sel:WORD_1
	v_pk_add_f32 v[38:39], v[160:161], v[38:39]
	v_pk_add_f32 v[40:41], v[188:189], v[40:41]
	v_pk_add_f32 v[34:35], v[190:191], v[34:35]
	v_pk_add_f32 v[36:37], v[228:229], v[36:37]
	v_cvt_pk_f16_f32 v37, v36, v37
	v_cvt_pk_f16_f32 v36, v34, v35
	v_cvt_pk_f16_f32 v35, v40, v41
	v_cvt_pk_f16_f32 v34, v38, v39
	global_store_dwordx4 v[238:239], v[34:37], off offset:256
	s_waitcnt vmcnt(11)
	v_cvt_f32_f16_e32 v160, v172
	v_cvt_f32_f16_sdwa v161, v172 dst_sel:DWORD dst_unused:UNUSED_PAD src0_sel:WORD_1
	v_cvt_f32_f16_e32 v188, v173
	v_cvt_f32_f16_sdwa v189, v173 dst_sel:DWORD dst_unused:UNUSED_PAD src0_sel:WORD_1
	v_cvt_f32_f16_e32 v190, v174
	v_cvt_f32_f16_sdwa v191, v174 dst_sel:DWORD dst_unused:UNUSED_PAD src0_sel:WORD_1
	v_cvt_f32_f16_e32 v228, v175
	v_cvt_f32_f16_sdwa v229, v175 dst_sel:DWORD dst_unused:UNUSED_PAD src0_sel:WORD_1
	v_pk_add_f32 v[30:31], v[160:161], v[30:31]
	v_pk_add_f32 v[32:33], v[188:189], v[32:33]
	v_pk_add_f32 v[26:27], v[190:191], v[26:27]
	v_pk_add_f32 v[28:29], v[228:229], v[28:29]
	v_cvt_pk_f16_f32 v29, v28, v29
	v_cvt_pk_f16_f32 v28, v26, v27
	v_cvt_pk_f16_f32 v27, v32, v33
	v_cvt_pk_f16_f32 v26, v30, v31
	global_store_dwordx4 v[240:241], v[26:29], off
	s_waitcnt vmcnt(10)
	v_cvt_f32_f16_e32 v160, v176
	v_cvt_f32_f16_sdwa v161, v176 dst_sel:DWORD dst_unused:UNUSED_PAD src0_sel:WORD_1
	v_cvt_f32_f16_e32 v188, v177
	v_cvt_f32_f16_sdwa v189, v177 dst_sel:DWORD dst_unused:UNUSED_PAD src0_sel:WORD_1
	v_cvt_f32_f16_e32 v190, v178
	v_cvt_f32_f16_sdwa v191, v178 dst_sel:DWORD dst_unused:UNUSED_PAD src0_sel:WORD_1
	v_cvt_f32_f16_e32 v228, v179
	v_cvt_f32_f16_sdwa v229, v179 dst_sel:DWORD dst_unused:UNUSED_PAD src0_sel:WORD_1
	v_pk_add_f32 v[22:23], v[160:161], v[22:23]
	v_pk_add_f32 v[24:25], v[188:189], v[24:25]
	v_pk_add_f32 v[18:19], v[190:191], v[18:19]
	v_pk_add_f32 v[20:21], v[228:229], v[20:21]
	v_cvt_pk_f16_f32 v21, v20, v21
	v_cvt_pk_f16_f32 v20, v18, v19
	v_cvt_pk_f16_f32 v19, v24, v25
	v_cvt_pk_f16_f32 v18, v22, v23
	global_store_dwordx4 v[240:241], v[18:21], off offset:256
	s_waitcnt vmcnt(9)
	v_cvt_f32_f16_e32 v160, v180
	v_cvt_f32_f16_sdwa v161, v180 dst_sel:DWORD dst_unused:UNUSED_PAD src0_sel:WORD_1
	v_cvt_f32_f16_e32 v188, v181
	v_cvt_f32_f16_sdwa v189, v181 dst_sel:DWORD dst_unused:UNUSED_PAD src0_sel:WORD_1
	v_cvt_f32_f16_e32 v190, v182
	v_cvt_f32_f16_sdwa v191, v182 dst_sel:DWORD dst_unused:UNUSED_PAD src0_sel:WORD_1
	v_cvt_f32_f16_e32 v228, v183
	v_cvt_f32_f16_sdwa v229, v183 dst_sel:DWORD dst_unused:UNUSED_PAD src0_sel:WORD_1
	v_pk_add_f32 v[14:15], v[160:161], v[14:15]
	v_pk_add_f32 v[16:17], v[188:189], v[16:17]
	v_pk_add_f32 v[10:11], v[190:191], v[10:11]
	v_pk_add_f32 v[12:13], v[228:229], v[12:13]
	v_cvt_pk_f16_f32 v13, v12, v13
	v_cvt_pk_f16_f32 v12, v10, v11
	v_cvt_pk_f16_f32 v11, v16, v17
	v_cvt_pk_f16_f32 v10, v14, v15
	global_store_dwordx4 v[242:243], v[10:13], off
	s_waitcnt vmcnt(8)
	v_cvt_f32_f16_e32 v160, v184
	v_cvt_f32_f16_sdwa v161, v184 dst_sel:DWORD dst_unused:UNUSED_PAD src0_sel:WORD_1
	v_cvt_f32_f16_e32 v188, v185
	v_cvt_f32_f16_sdwa v189, v185 dst_sel:DWORD dst_unused:UNUSED_PAD src0_sel:WORD_1
	v_cvt_f32_f16_e32 v190, v186
	v_cvt_f32_f16_sdwa v191, v186 dst_sel:DWORD dst_unused:UNUSED_PAD src0_sel:WORD_1
	v_cvt_f32_f16_e32 v228, v187
	v_cvt_f32_f16_sdwa v229, v187 dst_sel:DWORD dst_unused:UNUSED_PAD src0_sel:WORD_1
	v_pk_add_f32 v[6:7], v[160:161], v[6:7]
	v_pk_add_f32 v[8:9], v[188:189], v[8:9]
	v_pk_add_f32 v[2:3], v[190:191], v[2:3]
	v_pk_add_f32 v[4:5], v[228:229], v[4:5]
	v_cvt_pk_f16_f32 v5, v4, v5
	v_cvt_pk_f16_f32 v4, v2, v3
	v_cvt_pk_f16_f32 v3, v8, v9
	v_cvt_pk_f16_f32 v2, v6, v7
	global_store_dwordx4 v[242:243], v[2:5], off offset:256
	s_mov_b64 s[0:1], -1
	s_andn2_b64 vcc, exec, s[2:3]
	s_cbranch_vccnz .LBB0_987
	s_andn2_b64 vcc, exec, s[6:7]
	s_cbranch_vccnz .LBB0_986
	s_barrier
	s_branch .LBB0_986

.LBB0_1240:
	v_lshl_add_u32 v146, s75, 8, v1
	v_lshl_or_b32 v148, s86, 8, v163
	v_ashrrev_i32_e32 v147, 31, v146
	v_ashrrev_i32_e32 v149, 31, v148
	v_lshlrev_b64 v[150:151], 12, v[146:147]
	v_lshl_add_u64 v[150:151], s[64:65], 0, v[150:151]
	v_lshlrev_b64 v[148:149], 1, v[148:149]
	v_lshl_add_u64 v[150:151], v[150:151], 0, v[148:149]
	v_mov_b32_e32 v245, 0
	v_mov_b32_e32 v244, 0x10000
	v_lshl_add_u64 v[230:231], v[244:245], 0, v[150:151]
	v_mov_b32_e32 v244, 0x20000
	v_lshl_add_u64 v[232:233], v[244:245], 0, v[150:151]
	v_mov_b32_e32 v244, 0x30000
	v_lshl_add_u64 v[234:235], v[244:245], 0, v[150:151]
	v_mov_b32_e32 v244, 0x80000
	v_lshl_add_u64 v[236:237], v[244:245], 0, v[150:151]
	v_mov_b32_e32 v244, 0x90000
	v_lshl_add_u64 v[238:239], v[244:245], 0, v[150:151]
	v_mov_b32_e32 v244, 0xa0000
	v_lshl_add_u64 v[240:241], v[244:245], 0, v[150:151]
	v_mov_b32_e32 v244, 0xb0000
	v_lshl_add_u64 v[242:243], v[244:245], 0, v[150:151]
	global_load_dwordx4 v[146:149], v[150:151], off
	global_load_dwordx4 v[152:155], v[150:151], off offset:256
	global_load_dwordx4 v[156:159], v[230:231], off
	global_load_dwordx4 v[168:171], v[230:231], off offset:256
	global_load_dwordx4 v[172:175], v[232:233], off
	global_load_dwordx4 v[176:179], v[232:233], off offset:256
	global_load_dwordx4 v[180:183], v[234:235], off
	global_load_dwordx4 v[184:187], v[234:235], off offset:256
	s_waitcnt vmcnt(7)
	v_cvt_f32_f16_e32 v160, v146
	v_cvt_f32_f16_sdwa v161, v146 dst_sel:DWORD dst_unused:UNUSED_PAD src0_sel:WORD_1
	v_cvt_f32_f16_e32 v188, v147
	v_cvt_f32_f16_sdwa v189, v147 dst_sel:DWORD dst_unused:UNUSED_PAD src0_sel:WORD_1
	v_cvt_f32_f16_e32 v190, v148
	v_cvt_f32_f16_sdwa v191, v148 dst_sel:DWORD dst_unused:UNUSED_PAD src0_sel:WORD_1
	v_cvt_f32_f16_e32 v228, v149
	v_cvt_f32_f16_sdwa v229, v149 dst_sel:DWORD dst_unused:UNUSED_PAD src0_sel:WORD_1
	global_load_dwordx4 v[146:149], v[236:237], off
	v_pk_fma_f32 v[126:127], v[126:127], 0.5, v[160:161] op_sel_hi:[1,0,1]
	v_pk_fma_f32 v[128:129], v[128:129], 0.5, v[188:189] op_sel_hi:[1,0,1]
	v_pk_fma_f32 v[122:123], v[122:123], 0.5, v[190:191] op_sel_hi:[1,0,1]
	v_pk_fma_f32 v[124:125], v[124:125], 0.5, v[228:229] op_sel_hi:[1,0,1]
	v_cvt_pk_f16_f32 v125, v124, v125
	v_cvt_pk_f16_f32 v124, v122, v123
	v_cvt_pk_f16_f32 v123, v128, v129
	v_cvt_pk_f16_f32 v122, v126, v127
	global_store_dwordx4 v[150:151], v[122:125], off
	s_waitcnt vmcnt(8)
	v_cvt_f32_f16_e32 v160, v152
	v_cvt_f32_f16_sdwa v161, v152 dst_sel:DWORD dst_unused:UNUSED_PAD src0_sel:WORD_1
	v_cvt_f32_f16_e32 v188, v153
	v_cvt_f32_f16_sdwa v189, v153 dst_sel:DWORD dst_unused:UNUSED_PAD src0_sel:WORD_1
	v_cvt_f32_f16_e32 v190, v154
	v_cvt_f32_f16_sdwa v191, v154 dst_sel:DWORD dst_unused:UNUSED_PAD src0_sel:WORD_1
	v_cvt_f32_f16_e32 v228, v155
	v_cvt_f32_f16_sdwa v229, v155 dst_sel:DWORD dst_unused:UNUSED_PAD src0_sel:WORD_1
	global_load_dwordx4 v[152:155], v[236:237], off offset:256
	v_pk_fma_f32 v[118:119], v[118:119], 0.5, v[160:161] op_sel_hi:[1,0,1]
	v_pk_fma_f32 v[120:121], v[120:121], 0.5, v[188:189] op_sel_hi:[1,0,1]
	v_pk_fma_f32 v[114:115], v[114:115], 0.5, v[190:191] op_sel_hi:[1,0,1]
	v_pk_fma_f32 v[116:117], v[116:117], 0.5, v[228:229] op_sel_hi:[1,0,1]
	v_cvt_pk_f16_f32 v117, v116, v117
	v_cvt_pk_f16_f32 v116, v114, v115
	v_cvt_pk_f16_f32 v115, v120, v121
	v_cvt_pk_f16_f32 v114, v118, v119
	global_store_dwordx4 v[150:151], v[114:117], off offset:256
	s_waitcnt vmcnt(9)
	v_cvt_f32_f16_e32 v160, v156
	v_cvt_f32_f16_sdwa v161, v156 dst_sel:DWORD dst_unused:UNUSED_PAD src0_sel:WORD_1
	v_cvt_f32_f16_e32 v188, v157
	v_cvt_f32_f16_sdwa v189, v157 dst_sel:DWORD dst_unused:UNUSED_PAD src0_sel:WORD_1
	v_cvt_f32_f16_e32 v190, v158
	v_cvt_f32_f16_sdwa v191, v158 dst_sel:DWORD dst_unused:UNUSED_PAD src0_sel:WORD_1
	v_cvt_f32_f16_e32 v228, v159
	v_cvt_f32_f16_sdwa v229, v159 dst_sel:DWORD dst_unused:UNUSED_PAD src0_sel:WORD_1
	global_load_dwordx4 v[156:159], v[238:239], off
	v_pk_fma_f32 v[110:111], v[110:111], 0.5, v[160:161] op_sel_hi:[1,0,1]
	v_pk_fma_f32 v[112:113], v[112:113], 0.5, v[188:189] op_sel_hi:[1,0,1]
	v_pk_fma_f32 v[106:107], v[106:107], 0.5, v[190:191] op_sel_hi:[1,0,1]
	v_pk_fma_f32 v[108:109], v[108:109], 0.5, v[228:229] op_sel_hi:[1,0,1]
	v_cvt_pk_f16_f32 v109, v108, v109
	v_cvt_pk_f16_f32 v108, v106, v107
	v_cvt_pk_f16_f32 v107, v112, v113
	v_cvt_pk_f16_f32 v106, v110, v111
	global_store_dwordx4 v[230:231], v[106:109], off
	s_waitcnt vmcnt(10)
	v_cvt_f32_f16_e32 v160, v168
	v_cvt_f32_f16_sdwa v161, v168 dst_sel:DWORD dst_unused:UNUSED_PAD src0_sel:WORD_1
	v_cvt_f32_f16_e32 v188, v169
	v_cvt_f32_f16_sdwa v189, v169 dst_sel:DWORD dst_unused:UNUSED_PAD src0_sel:WORD_1
	v_cvt_f32_f16_e32 v190, v170
	v_cvt_f32_f16_sdwa v191, v170 dst_sel:DWORD dst_unused:UNUSED_PAD src0_sel:WORD_1
	v_cvt_f32_f16_e32 v228, v171
	v_cvt_f32_f16_sdwa v229, v171 dst_sel:DWORD dst_unused:UNUSED_PAD src0_sel:WORD_1
	global_load_dwordx4 v[168:171], v[238:239], off offset:256
	v_pk_fma_f32 v[102:103], v[102:103], 0.5, v[160:161] op_sel_hi:[1,0,1]
	v_pk_fma_f32 v[104:105], v[104:105], 0.5, v[188:189] op_sel_hi:[1,0,1]
	v_pk_fma_f32 v[98:99], v[98:99], 0.5, v[190:191] op_sel_hi:[1,0,1]
	v_pk_fma_f32 v[100:101], v[100:101], 0.5, v[228:229] op_sel_hi:[1,0,1]
	v_cvt_pk_f16_f32 v101, v100, v101
	v_cvt_pk_f16_f32 v100, v98, v99
	v_cvt_pk_f16_f32 v99, v104, v105
	v_cvt_pk_f16_f32 v98, v102, v103
	global_store_dwordx4 v[230:231], v[98:101], off offset:256
	s_waitcnt vmcnt(11)
	v_cvt_f32_f16_e32 v160, v172
	v_cvt_f32_f16_sdwa v161, v172 dst_sel:DWORD dst_unused:UNUSED_PAD src0_sel:WORD_1
	v_cvt_f32_f16_e32 v188, v173
	v_cvt_f32_f16_sdwa v189, v173 dst_sel:DWORD dst_unused:UNUSED_PAD src0_sel:WORD_1
	v_cvt_f32_f16_e32 v190, v174
	v_cvt_f32_f16_sdwa v191, v174 dst_sel:DWORD dst_unused:UNUSED_PAD src0_sel:WORD_1
	v_cvt_f32_f16_e32 v228, v175
	v_cvt_f32_f16_sdwa v229, v175 dst_sel:DWORD dst_unused:UNUSED_PAD src0_sel:WORD_1
	global_load_dwordx4 v[172:175], v[240:241], off
	v_pk_fma_f32 v[94:95], v[94:95], 0.5, v[160:161] op_sel_hi:[1,0,1]
	v_pk_fma_f32 v[96:97], v[96:97], 0.5, v[188:189] op_sel_hi:[1,0,1]
	v_pk_fma_f32 v[90:91], v[90:91], 0.5, v[190:191] op_sel_hi:[1,0,1]
	v_pk_fma_f32 v[92:93], v[92:93], 0.5, v[228:229] op_sel_hi:[1,0,1]
	v_cvt_pk_f16_f32 v93, v92, v93
	v_cvt_pk_f16_f32 v92, v90, v91
	v_cvt_pk_f16_f32 v91, v96, v97
	v_cvt_pk_f16_f32 v90, v94, v95
	global_store_dwordx4 v[232:233], v[90:93], off
	s_waitcnt vmcnt(12)
	v_cvt_f32_f16_e32 v160, v176
	v_cvt_f32_f16_sdwa v161, v176 dst_sel:DWORD dst_unused:UNUSED_PAD src0_sel:WORD_1
	v_cvt_f32_f16_e32 v188, v177
	v_cvt_f32_f16_sdwa v189, v177 dst_sel:DWORD dst_unused:UNUSED_PAD src0_sel:WORD_1
	v_cvt_f32_f16_e32 v190, v178
	v_cvt_f32_f16_sdwa v191, v178 dst_sel:DWORD dst_unused:UNUSED_PAD src0_sel:WORD_1
	v_cvt_f32_f16_e32 v228, v179
	v_cvt_f32_f16_sdwa v229, v179 dst_sel:DWORD dst_unused:UNUSED_PAD src0_sel:WORD_1
	global_load_dwordx4 v[176:179], v[240:241], off offset:256
	v_pk_fma_f32 v[86:87], v[86:87], 0.5, v[160:161] op_sel_hi:[1,0,1]
	v_pk_fma_f32 v[88:89], v[88:89], 0.5, v[188:189] op_sel_hi:[1,0,1]
	v_pk_fma_f32 v[82:83], v[82:83], 0.5, v[190:191] op_sel_hi:[1,0,1]
	v_pk_fma_f32 v[84:85], v[84:85], 0.5, v[228:229] op_sel_hi:[1,0,1]
	v_cvt_pk_f16_f32 v85, v84, v85
	v_cvt_pk_f16_f32 v84, v82, v83
	v_cvt_pk_f16_f32 v83, v88, v89
	v_cvt_pk_f16_f32 v82, v86, v87
	global_store_dwordx4 v[232:233], v[82:85], off offset:256
	s_waitcnt vmcnt(13)
	v_cvt_f32_f16_e32 v160, v180
	v_cvt_f32_f16_sdwa v161, v180 dst_sel:DWORD dst_unused:UNUSED_PAD src0_sel:WORD_1
	v_cvt_f32_f16_e32 v188, v181
	v_cvt_f32_f16_sdwa v189, v181 dst_sel:DWORD dst_unused:UNUSED_PAD src0_sel:WORD_1
	v_cvt_f32_f16_e32 v190, v182
	v_cvt_f32_f16_sdwa v191, v182 dst_sel:DWORD dst_unused:UNUSED_PAD src0_sel:WORD_1
	v_cvt_f32_f16_e32 v228, v183
	v_cvt_f32_f16_sdwa v229, v183 dst_sel:DWORD dst_unused:UNUSED_PAD src0_sel:WORD_1
	global_load_dwordx4 v[180:183], v[242:243], off
	v_pk_fma_f32 v[78:79], v[78:79], 0.5, v[160:161] op_sel_hi:[1,0,1]
	v_pk_fma_f32 v[80:81], v[80:81], 0.5, v[188:189] op_sel_hi:[1,0,1]
	v_pk_fma_f32 v[74:75], v[74:75], 0.5, v[190:191] op_sel_hi:[1,0,1]
	v_pk_fma_f32 v[76:77], v[76:77], 0.5, v[228:229] op_sel_hi:[1,0,1]
	v_cvt_pk_f16_f32 v77, v76, v77
	v_cvt_pk_f16_f32 v76, v74, v75
	v_cvt_pk_f16_f32 v75, v80, v81
	v_cvt_pk_f16_f32 v74, v78, v79
	global_store_dwordx4 v[234:235], v[74:77], off
	s_waitcnt vmcnt(14)
	v_cvt_f32_f16_e32 v160, v184
	v_cvt_f32_f16_sdwa v161, v184 dst_sel:DWORD dst_unused:UNUSED_PAD src0_sel:WORD_1
	v_cvt_f32_f16_e32 v188, v185
	v_cvt_f32_f16_sdwa v189, v185 dst_sel:DWORD dst_unused:UNUSED_PAD src0_sel:WORD_1
	v_cvt_f32_f16_e32 v190, v186
	v_cvt_f32_f16_sdwa v191, v186 dst_sel:DWORD dst_unused:UNUSED_PAD src0_sel:WORD_1
	v_cvt_f32_f16_e32 v228, v187
	v_cvt_f32_f16_sdwa v229, v187 dst_sel:DWORD dst_unused:UNUSED_PAD src0_sel:WORD_1
	global_load_dwordx4 v[184:187], v[242:243], off offset:256
	v_pk_fma_f32 v[70:71], v[70:71], 0.5, v[160:161] op_sel_hi:[1,0,1]
	v_pk_fma_f32 v[72:73], v[72:73], 0.5, v[188:189] op_sel_hi:[1,0,1]
	v_pk_fma_f32 v[66:67], v[66:67], 0.5, v[190:191] op_sel_hi:[1,0,1]
	v_pk_fma_f32 v[68:69], v[68:69], 0.5, v[228:229] op_sel_hi:[1,0,1]
	v_cvt_pk_f16_f32 v69, v68, v69
	v_cvt_pk_f16_f32 v68, v66, v67
	v_cvt_pk_f16_f32 v67, v72, v73
	v_cvt_pk_f16_f32 v66, v70, v71
	global_store_dwordx4 v[234:235], v[66:69], off offset:256
	s_waitcnt vmcnt(15)
	v_cvt_f32_f16_e32 v160, v146
	v_cvt_f32_f16_sdwa v161, v146 dst_sel:DWORD dst_unused:UNUSED_PAD src0_sel:WORD_1
	v_cvt_f32_f16_e32 v188, v147
	v_cvt_f32_f16_sdwa v189, v147 dst_sel:DWORD dst_unused:UNUSED_PAD src0_sel:WORD_1
	v_cvt_f32_f16_e32 v190, v148
	v_cvt_f32_f16_sdwa v191, v148 dst_sel:DWORD dst_unused:UNUSED_PAD src0_sel:WORD_1
	v_cvt_f32_f16_e32 v228, v149
	v_cvt_f32_f16_sdwa v229, v149 dst_sel:DWORD dst_unused:UNUSED_PAD src0_sel:WORD_1
	v_pk_fma_f32 v[62:63], v[62:63], 0.5, v[160:161] op_sel_hi:[1,0,1]
	v_pk_fma_f32 v[64:65], v[64:65], 0.5, v[188:189] op_sel_hi:[1,0,1]
	v_pk_fma_f32 v[58:59], v[58:59], 0.5, v[190:191] op_sel_hi:[1,0,1]
	v_pk_fma_f32 v[60:61], v[60:61], 0.5, v[228:229] op_sel_hi:[1,0,1]
	v_cvt_pk_f16_f32 v61, v60, v61
	v_cvt_pk_f16_f32 v60, v58, v59
	v_cvt_pk_f16_f32 v59, v64, v65
	v_cvt_pk_f16_f32 v58, v62, v63
	global_store_dwordx4 v[236:237], v[58:61], off
	s_waitcnt vmcnt(14)
	v_cvt_f32_f16_e32 v160, v152
	v_cvt_f32_f16_sdwa v161, v152 dst_sel:DWORD dst_unused:UNUSED_PAD src0_sel:WORD_1
	v_cvt_f32_f16_e32 v188, v153
	v_cvt_f32_f16_sdwa v189, v153 dst_sel:DWORD dst_unused:UNUSED_PAD src0_sel:WORD_1
	v_cvt_f32_f16_e32 v190, v154
	v_cvt_f32_f16_sdwa v191, v154 dst_sel:DWORD dst_unused:UNUSED_PAD src0_sel:WORD_1
	v_cvt_f32_f16_e32 v228, v155
	v_cvt_f32_f16_sdwa v229, v155 dst_sel:DWORD dst_unused:UNUSED_PAD src0_sel:WORD_1
	v_pk_fma_f32 v[54:55], v[54:55], 0.5, v[160:161] op_sel_hi:[1,0,1]
	v_pk_fma_f32 v[56:57], v[56:57], 0.5, v[188:189] op_sel_hi:[1,0,1]
	v_pk_fma_f32 v[50:51], v[50:51], 0.5, v[190:191] op_sel_hi:[1,0,1]
	v_pk_fma_f32 v[52:53], v[52:53], 0.5, v[228:229] op_sel_hi:[1,0,1]
	v_cvt_pk_f16_f32 v53, v52, v53
	v_cvt_pk_f16_f32 v52, v50, v51
	v_cvt_pk_f16_f32 v51, v56, v57
	v_cvt_pk_f16_f32 v50, v54, v55
	global_store_dwordx4 v[236:237], v[50:53], off offset:256
	s_waitcnt vmcnt(13)
	v_cvt_f32_f16_e32 v160, v156
	v_cvt_f32_f16_sdwa v161, v156 dst_sel:DWORD dst_unused:UNUSED_PAD src0_sel:WORD_1
	v_cvt_f32_f16_e32 v188, v157
	v_cvt_f32_f16_sdwa v189, v157 dst_sel:DWORD dst_unused:UNUSED_PAD src0_sel:WORD_1
	v_cvt_f32_f16_e32 v190, v158
	v_cvt_f32_f16_sdwa v191, v158 dst_sel:DWORD dst_unused:UNUSED_PAD src0_sel:WORD_1
	v_cvt_f32_f16_e32 v228, v159
	v_cvt_f32_f16_sdwa v229, v159 dst_sel:DWORD dst_unused:UNUSED_PAD src0_sel:WORD_1
	v_pk_fma_f32 v[46:47], v[46:47], 0.5, v[160:161] op_sel_hi:[1,0,1]
	v_pk_fma_f32 v[48:49], v[48:49], 0.5, v[188:189] op_sel_hi:[1,0,1]
	v_pk_fma_f32 v[42:43], v[42:43], 0.5, v[190:191] op_sel_hi:[1,0,1]
	v_pk_fma_f32 v[44:45], v[44:45], 0.5, v[228:229] op_sel_hi:[1,0,1]
	v_cvt_pk_f16_f32 v45, v44, v45
	v_cvt_pk_f16_f32 v44, v42, v43
	v_cvt_pk_f16_f32 v43, v48, v49
	v_cvt_pk_f16_f32 v42, v46, v47
	global_store_dwordx4 v[238:239], v[42:45], off
	s_waitcnt vmcnt(12)
	v_cvt_f32_f16_e32 v160, v168
	v_cvt_f32_f16_sdwa v161, v168 dst_sel:DWORD dst_unused:UNUSED_PAD src0_sel:WORD_1
	v_cvt_f32_f16_e32 v188, v169
	v_cvt_f32_f16_sdwa v189, v169 dst_sel:DWORD dst_unused:UNUSED_PAD src0_sel:WORD_1
	v_cvt_f32_f16_e32 v190, v170
	v_cvt_f32_f16_sdwa v191, v170 dst_sel:DWORD dst_unused:UNUSED_PAD src0_sel:WORD_1
	v_cvt_f32_f16_e32 v228, v171
	v_cvt_f32_f16_sdwa v229, v171 dst_sel:DWORD dst_unused:UNUSED_PAD src0_sel:WORD_1
	v_pk_fma_f32 v[38:39], v[38:39], 0.5, v[160:161] op_sel_hi:[1,0,1]
	v_pk_fma_f32 v[40:41], v[40:41], 0.5, v[188:189] op_sel_hi:[1,0,1]
	v_pk_fma_f32 v[34:35], v[34:35], 0.5, v[190:191] op_sel_hi:[1,0,1]
	v_pk_fma_f32 v[36:37], v[36:37], 0.5, v[228:229] op_sel_hi:[1,0,1]
	v_cvt_pk_f16_f32 v37, v36, v37
	v_cvt_pk_f16_f32 v36, v34, v35
	v_cvt_pk_f16_f32 v35, v40, v41
	v_cvt_pk_f16_f32 v34, v38, v39
	global_store_dwordx4 v[238:239], v[34:37], off offset:256
	s_waitcnt vmcnt(11)
	v_cvt_f32_f16_e32 v160, v172
	v_cvt_f32_f16_sdwa v161, v172 dst_sel:DWORD dst_unused:UNUSED_PAD src0_sel:WORD_1
	v_cvt_f32_f16_e32 v188, v173
	v_cvt_f32_f16_sdwa v189, v173 dst_sel:DWORD dst_unused:UNUSED_PAD src0_sel:WORD_1
	v_cvt_f32_f16_e32 v190, v174
	v_cvt_f32_f16_sdwa v191, v174 dst_sel:DWORD dst_unused:UNUSED_PAD src0_sel:WORD_1
	v_cvt_f32_f16_e32 v228, v175
	v_cvt_f32_f16_sdwa v229, v175 dst_sel:DWORD dst_unused:UNUSED_PAD src0_sel:WORD_1
	v_pk_fma_f32 v[30:31], v[30:31], 0.5, v[160:161] op_sel_hi:[1,0,1]
	v_pk_fma_f32 v[32:33], v[32:33], 0.5, v[188:189] op_sel_hi:[1,0,1]
	v_pk_fma_f32 v[26:27], v[26:27], 0.5, v[190:191] op_sel_hi:[1,0,1]
	v_pk_fma_f32 v[28:29], v[28:29], 0.5, v[228:229] op_sel_hi:[1,0,1]
	v_cvt_pk_f16_f32 v29, v28, v29
	v_cvt_pk_f16_f32 v28, v26, v27
	v_cvt_pk_f16_f32 v27, v32, v33
	v_cvt_pk_f16_f32 v26, v30, v31
	global_store_dwordx4 v[240:241], v[26:29], off
	s_waitcnt vmcnt(10)
	v_cvt_f32_f16_e32 v160, v176
	v_cvt_f32_f16_sdwa v161, v176 dst_sel:DWORD dst_unused:UNUSED_PAD src0_sel:WORD_1
	v_cvt_f32_f16_e32 v188, v177
	v_cvt_f32_f16_sdwa v189, v177 dst_sel:DWORD dst_unused:UNUSED_PAD src0_sel:WORD_1
	v_cvt_f32_f16_e32 v190, v178
	v_cvt_f32_f16_sdwa v191, v178 dst_sel:DWORD dst_unused:UNUSED_PAD src0_sel:WORD_1
	v_cvt_f32_f16_e32 v228, v179
	v_cvt_f32_f16_sdwa v229, v179 dst_sel:DWORD dst_unused:UNUSED_PAD src0_sel:WORD_1
	v_pk_fma_f32 v[22:23], v[22:23], 0.5, v[160:161] op_sel_hi:[1,0,1]
	v_pk_fma_f32 v[24:25], v[24:25], 0.5, v[188:189] op_sel_hi:[1,0,1]
	v_pk_fma_f32 v[18:19], v[18:19], 0.5, v[190:191] op_sel_hi:[1,0,1]
	v_pk_fma_f32 v[20:21], v[20:21], 0.5, v[228:229] op_sel_hi:[1,0,1]
	v_cvt_pk_f16_f32 v21, v20, v21
	v_cvt_pk_f16_f32 v20, v18, v19
	v_cvt_pk_f16_f32 v19, v24, v25
	v_cvt_pk_f16_f32 v18, v22, v23
	global_store_dwordx4 v[240:241], v[18:21], off offset:256
	s_waitcnt vmcnt(9)
	v_cvt_f32_f16_e32 v160, v180
	v_cvt_f32_f16_sdwa v161, v180 dst_sel:DWORD dst_unused:UNUSED_PAD src0_sel:WORD_1
	v_cvt_f32_f16_e32 v188, v181
	v_cvt_f32_f16_sdwa v189, v181 dst_sel:DWORD dst_unused:UNUSED_PAD src0_sel:WORD_1
	v_cvt_f32_f16_e32 v190, v182
	v_cvt_f32_f16_sdwa v191, v182 dst_sel:DWORD dst_unused:UNUSED_PAD src0_sel:WORD_1
	v_cvt_f32_f16_e32 v228, v183
	v_cvt_f32_f16_sdwa v229, v183 dst_sel:DWORD dst_unused:UNUSED_PAD src0_sel:WORD_1
	v_pk_fma_f32 v[14:15], v[14:15], 0.5, v[160:161] op_sel_hi:[1,0,1]
	v_pk_fma_f32 v[16:17], v[16:17], 0.5, v[188:189] op_sel_hi:[1,0,1]
	v_pk_fma_f32 v[10:11], v[10:11], 0.5, v[190:191] op_sel_hi:[1,0,1]
	v_pk_fma_f32 v[12:13], v[12:13], 0.5, v[228:229] op_sel_hi:[1,0,1]
	v_cvt_pk_f16_f32 v13, v12, v13
	v_cvt_pk_f16_f32 v12, v10, v11
	v_cvt_pk_f16_f32 v11, v16, v17
	v_cvt_pk_f16_f32 v10, v14, v15
	global_store_dwordx4 v[242:243], v[10:13], off
	s_waitcnt vmcnt(8)
	v_cvt_f32_f16_e32 v160, v184
	v_cvt_f32_f16_sdwa v161, v184 dst_sel:DWORD dst_unused:UNUSED_PAD src0_sel:WORD_1
	v_cvt_f32_f16_e32 v188, v185
	v_cvt_f32_f16_sdwa v189, v185 dst_sel:DWORD dst_unused:UNUSED_PAD src0_sel:WORD_1
	v_cvt_f32_f16_e32 v190, v186
	v_cvt_f32_f16_sdwa v191, v186 dst_sel:DWORD dst_unused:UNUSED_PAD src0_sel:WORD_1
	v_cvt_f32_f16_e32 v228, v187
	v_cvt_f32_f16_sdwa v229, v187 dst_sel:DWORD dst_unused:UNUSED_PAD src0_sel:WORD_1
	v_pk_fma_f32 v[6:7], v[6:7], 0.5, v[160:161] op_sel_hi:[1,0,1]
	v_pk_fma_f32 v[8:9], v[8:9], 0.5, v[188:189] op_sel_hi:[1,0,1]
	v_pk_fma_f32 v[2:3], v[2:3], 0.5, v[190:191] op_sel_hi:[1,0,1]
	v_pk_fma_f32 v[4:5], v[4:5], 0.5, v[228:229] op_sel_hi:[1,0,1]
	v_cvt_pk_f16_f32 v5, v4, v5
	v_cvt_pk_f16_f32 v4, v2, v3
	v_cvt_pk_f16_f32 v3, v8, v9
	v_cvt_pk_f16_f32 v2, v6, v7
	global_store_dwordx4 v[242:243], v[2:5], off offset:256
	s_mov_b64 s[0:1], -1
	s_and_b64 vcc, exec, s[2:3]
	s_cbranch_vccnz .LBB0_1225
	s_andn2_b64 vcc, exec, s[8:9]
	s_cbranch_vccnz .LBB0_1224
	s_barrier
	s_branch .LBB0_1224

.LBB0_2092:
	v_lshl_or_b32 v130, s74, 8, v177
	v_lshl_add_u32 v162, s73, 8, v1
	v_ashrrev_i32_e32 v131, 31, v130
	v_lshlrev_b64 v[164:165], 1, v[130:131]
	v_or_b32_e32 v130, 16, v162
	v_ashrrev_i32_e32 v163, 31, v162
	v_ashrrev_i32_e32 v131, 31, v130
	v_lshlrev_b64 v[132:133], 12, v[162:163]
	v_lshlrev_b64 v[130:131], 12, v[130:131]
	v_lshl_add_u64 v[132:133], s[64:65], 0, v[132:133]
	v_lshl_add_u64 v[130:131], s[64:65], 0, v[130:131]
	v_lshl_add_u64 v[174:175], v[132:133], 0, v[164:165]
	v_lshl_add_u64 v[172:173], v[130:131], 0, v[164:165]
	v_mov_b32_e32 v209, 0
	v_mov_b32_e32 v208, 0x10000
	v_lshl_add_u64 v[194:195], v[208:209], 0, v[174:175]
	v_mov_b32_e32 v208, 0x20000
	v_lshl_add_u64 v[196:197], v[208:209], 0, v[174:175]
	v_mov_b32_e32 v208, 0x30000
	v_lshl_add_u64 v[198:199], v[208:209], 0, v[174:175]
	v_mov_b32_e32 v208, 0x80000
	v_lshl_add_u64 v[200:201], v[208:209], 0, v[174:175]
	v_mov_b32_e32 v208, 0x90000
	v_lshl_add_u64 v[202:203], v[208:209], 0, v[174:175]
	v_mov_b32_e32 v208, 0xa0000
	v_lshl_add_u64 v[204:205], v[208:209], 0, v[174:175]
	v_mov_b32_e32 v208, 0xb0000
	v_lshl_add_u64 v[206:207], v[208:209], 0, v[174:175]
	global_load_dwordx4 v[130:133], v[174:175], off
	global_load_dwordx4 v[134:137], v[174:175], off offset:256
	global_load_dwordx4 v[138:141], v[194:195], off
	global_load_dwordx4 v[142:145], v[194:195], off offset:256
	global_load_dwordx4 v[162:165], v[196:197], off
	global_load_dwordx4 v[166:169], v[196:197], off offset:256
	global_load_dwordx4 v[170:173], v[198:199], off
	global_load_dwordx4 v[182:185], v[198:199], off offset:256
	s_waitcnt vmcnt(7)
	v_cvt_f32_f16_e32 v186, v130
	v_cvt_f32_f16_sdwa v187, v130 dst_sel:DWORD dst_unused:UNUSED_PAD src0_sel:WORD_1
	v_cvt_f32_f16_e32 v188, v131
	v_cvt_f32_f16_sdwa v189, v131 dst_sel:DWORD dst_unused:UNUSED_PAD src0_sel:WORD_1
	v_cvt_f32_f16_e32 v190, v132
	v_cvt_f32_f16_sdwa v191, v132 dst_sel:DWORD dst_unused:UNUSED_PAD src0_sel:WORD_1
	v_cvt_f32_f16_e32 v192, v133
	v_cvt_f32_f16_sdwa v193, v133 dst_sel:DWORD dst_unused:UNUSED_PAD src0_sel:WORD_1
	global_load_dwordx4 v[130:133], v[200:201], off
	v_pk_fma_f32 v[126:127], v[126:127], 0.5, v[186:187] op_sel_hi:[1,0,1]
	v_pk_fma_f32 v[128:129], v[128:129], 0.5, v[188:189] op_sel_hi:[1,0,1]
	v_pk_fma_f32 v[122:123], v[122:123], 0.5, v[190:191] op_sel_hi:[1,0,1]
	v_pk_fma_f32 v[124:125], v[124:125], 0.5, v[192:193] op_sel_hi:[1,0,1]
	v_cvt_pk_f16_f32 v125, v124, v125
	v_cvt_pk_f16_f32 v124, v122, v123
	v_cvt_pk_f16_f32 v123, v128, v129
	v_cvt_pk_f16_f32 v122, v126, v127
	global_store_dwordx4 v[174:175], v[122:125], off
	s_waitcnt vmcnt(8)
	v_cvt_f32_f16_e32 v186, v134
	v_cvt_f32_f16_sdwa v187, v134 dst_sel:DWORD dst_unused:UNUSED_PAD src0_sel:WORD_1
	v_cvt_f32_f16_e32 v188, v135
	v_cvt_f32_f16_sdwa v189, v135 dst_sel:DWORD dst_unused:UNUSED_PAD src0_sel:WORD_1
	v_cvt_f32_f16_e32 v190, v136
	v_cvt_f32_f16_sdwa v191, v136 dst_sel:DWORD dst_unused:UNUSED_PAD src0_sel:WORD_1
	v_cvt_f32_f16_e32 v192, v137
	v_cvt_f32_f16_sdwa v193, v137 dst_sel:DWORD dst_unused:UNUSED_PAD src0_sel:WORD_1
	global_load_dwordx4 v[134:137], v[200:201], off offset:256
	v_pk_fma_f32 v[118:119], v[118:119], 0.5, v[186:187] op_sel_hi:[1,0,1]
	v_pk_fma_f32 v[120:121], v[120:121], 0.5, v[188:189] op_sel_hi:[1,0,1]
	v_pk_fma_f32 v[114:115], v[114:115], 0.5, v[190:191] op_sel_hi:[1,0,1]
	v_pk_fma_f32 v[116:117], v[116:117], 0.5, v[192:193] op_sel_hi:[1,0,1]
	v_cvt_pk_f16_f32 v117, v116, v117
	v_cvt_pk_f16_f32 v116, v114, v115
	v_cvt_pk_f16_f32 v115, v120, v121
	v_cvt_pk_f16_f32 v114, v118, v119
	global_store_dwordx4 v[174:175], v[114:117], off offset:256
	s_waitcnt vmcnt(9)
	v_cvt_f32_f16_e32 v186, v138
	v_cvt_f32_f16_sdwa v187, v138 dst_sel:DWORD dst_unused:UNUSED_PAD src0_sel:WORD_1
	v_cvt_f32_f16_e32 v188, v139
	v_cvt_f32_f16_sdwa v189, v139 dst_sel:DWORD dst_unused:UNUSED_PAD src0_sel:WORD_1
	v_cvt_f32_f16_e32 v190, v140
	v_cvt_f32_f16_sdwa v191, v140 dst_sel:DWORD dst_unused:UNUSED_PAD src0_sel:WORD_1
	v_cvt_f32_f16_e32 v192, v141
	v_cvt_f32_f16_sdwa v193, v141 dst_sel:DWORD dst_unused:UNUSED_PAD src0_sel:WORD_1
	global_load_dwordx4 v[138:141], v[202:203], off
	v_pk_fma_f32 v[110:111], v[110:111], 0.5, v[186:187] op_sel_hi:[1,0,1]
	v_pk_fma_f32 v[112:113], v[112:113], 0.5, v[188:189] op_sel_hi:[1,0,1]
	v_pk_fma_f32 v[106:107], v[106:107], 0.5, v[190:191] op_sel_hi:[1,0,1]
	v_pk_fma_f32 v[108:109], v[108:109], 0.5, v[192:193] op_sel_hi:[1,0,1]
	v_cvt_pk_f16_f32 v109, v108, v109
	v_cvt_pk_f16_f32 v108, v106, v107
	v_cvt_pk_f16_f32 v107, v112, v113
	v_cvt_pk_f16_f32 v106, v110, v111
	global_store_dwordx4 v[194:195], v[106:109], off
	s_waitcnt vmcnt(10)
	v_cvt_f32_f16_e32 v186, v142
	v_cvt_f32_f16_sdwa v187, v142 dst_sel:DWORD dst_unused:UNUSED_PAD src0_sel:WORD_1
	v_cvt_f32_f16_e32 v188, v143
	v_cvt_f32_f16_sdwa v189, v143 dst_sel:DWORD dst_unused:UNUSED_PAD src0_sel:WORD_1
	v_cvt_f32_f16_e32 v190, v144
	v_cvt_f32_f16_sdwa v191, v144 dst_sel:DWORD dst_unused:UNUSED_PAD src0_sel:WORD_1
	v_cvt_f32_f16_e32 v192, v145
	v_cvt_f32_f16_sdwa v193, v145 dst_sel:DWORD dst_unused:UNUSED_PAD src0_sel:WORD_1
	global_load_dwordx4 v[142:145], v[202:203], off offset:256
	v_pk_fma_f32 v[102:103], v[102:103], 0.5, v[186:187] op_sel_hi:[1,0,1]
	v_pk_fma_f32 v[104:105], v[104:105], 0.5, v[188:189] op_sel_hi:[1,0,1]
	v_pk_fma_f32 v[98:99], v[98:99], 0.5, v[190:191] op_sel_hi:[1,0,1]
	v_pk_fma_f32 v[100:101], v[100:101], 0.5, v[192:193] op_sel_hi:[1,0,1]
	v_cvt_pk_f16_f32 v101, v100, v101
	v_cvt_pk_f16_f32 v100, v98, v99
	v_cvt_pk_f16_f32 v99, v104, v105
	v_cvt_pk_f16_f32 v98, v102, v103
	global_store_dwordx4 v[194:195], v[98:101], off offset:256
	s_waitcnt vmcnt(11)
	v_cvt_f32_f16_e32 v186, v162
	v_cvt_f32_f16_sdwa v187, v162 dst_sel:DWORD dst_unused:UNUSED_PAD src0_sel:WORD_1
	v_cvt_f32_f16_e32 v188, v163
	v_cvt_f32_f16_sdwa v189, v163 dst_sel:DWORD dst_unused:UNUSED_PAD src0_sel:WORD_1
	v_cvt_f32_f16_e32 v190, v164
	v_cvt_f32_f16_sdwa v191, v164 dst_sel:DWORD dst_unused:UNUSED_PAD src0_sel:WORD_1
	v_cvt_f32_f16_e32 v192, v165
	v_cvt_f32_f16_sdwa v193, v165 dst_sel:DWORD dst_unused:UNUSED_PAD src0_sel:WORD_1
	global_load_dwordx4 v[162:165], v[204:205], off
	v_pk_fma_f32 v[94:95], v[94:95], 0.5, v[186:187] op_sel_hi:[1,0,1]
	v_pk_fma_f32 v[96:97], v[96:97], 0.5, v[188:189] op_sel_hi:[1,0,1]
	v_pk_fma_f32 v[90:91], v[90:91], 0.5, v[190:191] op_sel_hi:[1,0,1]
	v_pk_fma_f32 v[92:93], v[92:93], 0.5, v[192:193] op_sel_hi:[1,0,1]
	v_cvt_pk_f16_f32 v93, v92, v93
	v_cvt_pk_f16_f32 v92, v90, v91
	v_cvt_pk_f16_f32 v91, v96, v97
	v_cvt_pk_f16_f32 v90, v94, v95
	global_store_dwordx4 v[196:197], v[90:93], off
	s_waitcnt vmcnt(12)
	v_cvt_f32_f16_e32 v186, v166
	v_cvt_f32_f16_sdwa v187, v166 dst_sel:DWORD dst_unused:UNUSED_PAD src0_sel:WORD_1
	v_cvt_f32_f16_e32 v188, v167
	v_cvt_f32_f16_sdwa v189, v167 dst_sel:DWORD dst_unused:UNUSED_PAD src0_sel:WORD_1
	v_cvt_f32_f16_e32 v190, v168
	v_cvt_f32_f16_sdwa v191, v168 dst_sel:DWORD dst_unused:UNUSED_PAD src0_sel:WORD_1
	v_cvt_f32_f16_e32 v192, v169
	v_cvt_f32_f16_sdwa v193, v169 dst_sel:DWORD dst_unused:UNUSED_PAD src0_sel:WORD_1
	global_load_dwordx4 v[166:169], v[204:205], off offset:256
	v_pk_fma_f32 v[86:87], v[86:87], 0.5, v[186:187] op_sel_hi:[1,0,1]
	v_pk_fma_f32 v[88:89], v[88:89], 0.5, v[188:189] op_sel_hi:[1,0,1]
	v_pk_fma_f32 v[82:83], v[82:83], 0.5, v[190:191] op_sel_hi:[1,0,1]
	v_pk_fma_f32 v[84:85], v[84:85], 0.5, v[192:193] op_sel_hi:[1,0,1]
	v_cvt_pk_f16_f32 v85, v84, v85
	v_cvt_pk_f16_f32 v84, v82, v83
	v_cvt_pk_f16_f32 v83, v88, v89
	v_cvt_pk_f16_f32 v82, v86, v87
	global_store_dwordx4 v[196:197], v[82:85], off offset:256
	s_waitcnt vmcnt(13)
	v_cvt_f32_f16_e32 v186, v170
	v_cvt_f32_f16_sdwa v187, v170 dst_sel:DWORD dst_unused:UNUSED_PAD src0_sel:WORD_1
	v_cvt_f32_f16_e32 v188, v171
	v_cvt_f32_f16_sdwa v189, v171 dst_sel:DWORD dst_unused:UNUSED_PAD src0_sel:WORD_1
	v_cvt_f32_f16_e32 v190, v172
	v_cvt_f32_f16_sdwa v191, v172 dst_sel:DWORD dst_unused:UNUSED_PAD src0_sel:WORD_1
	v_cvt_f32_f16_e32 v192, v173
	v_cvt_f32_f16_sdwa v193, v173 dst_sel:DWORD dst_unused:UNUSED_PAD src0_sel:WORD_1
	global_load_dwordx4 v[170:173], v[206:207], off
	v_pk_fma_f32 v[78:79], v[78:79], 0.5, v[186:187] op_sel_hi:[1,0,1]
	v_pk_fma_f32 v[80:81], v[80:81], 0.5, v[188:189] op_sel_hi:[1,0,1]
	v_pk_fma_f32 v[74:75], v[74:75], 0.5, v[190:191] op_sel_hi:[1,0,1]
	v_pk_fma_f32 v[76:77], v[76:77], 0.5, v[192:193] op_sel_hi:[1,0,1]
	v_cvt_pk_f16_f32 v77, v76, v77
	v_cvt_pk_f16_f32 v76, v74, v75
	v_cvt_pk_f16_f32 v75, v80, v81
	v_cvt_pk_f16_f32 v74, v78, v79
	global_store_dwordx4 v[198:199], v[74:77], off
	s_waitcnt vmcnt(14)
	v_cvt_f32_f16_e32 v186, v182
	v_cvt_f32_f16_sdwa v187, v182 dst_sel:DWORD dst_unused:UNUSED_PAD src0_sel:WORD_1
	v_cvt_f32_f16_e32 v188, v183
	v_cvt_f32_f16_sdwa v189, v183 dst_sel:DWORD dst_unused:UNUSED_PAD src0_sel:WORD_1
	v_cvt_f32_f16_e32 v190, v184
	v_cvt_f32_f16_sdwa v191, v184 dst_sel:DWORD dst_unused:UNUSED_PAD src0_sel:WORD_1
	v_cvt_f32_f16_e32 v192, v185
	v_cvt_f32_f16_sdwa v193, v185 dst_sel:DWORD dst_unused:UNUSED_PAD src0_sel:WORD_1
	global_load_dwordx4 v[182:185], v[206:207], off offset:256
	v_pk_fma_f32 v[70:71], v[70:71], 0.5, v[186:187] op_sel_hi:[1,0,1]
	v_pk_fma_f32 v[72:73], v[72:73], 0.5, v[188:189] op_sel_hi:[1,0,1]
	v_pk_fma_f32 v[66:67], v[66:67], 0.5, v[190:191] op_sel_hi:[1,0,1]
	v_pk_fma_f32 v[68:69], v[68:69], 0.5, v[192:193] op_sel_hi:[1,0,1]
	v_cvt_pk_f16_f32 v69, v68, v69
	v_cvt_pk_f16_f32 v68, v66, v67
	v_cvt_pk_f16_f32 v67, v72, v73
	v_cvt_pk_f16_f32 v66, v70, v71
	global_store_dwordx4 v[198:199], v[66:69], off offset:256
	s_waitcnt vmcnt(15)
	v_cvt_f32_f16_e32 v186, v130
	v_cvt_f32_f16_sdwa v187, v130 dst_sel:DWORD dst_unused:UNUSED_PAD src0_sel:WORD_1
	v_cvt_f32_f16_e32 v188, v131
	v_cvt_f32_f16_sdwa v189, v131 dst_sel:DWORD dst_unused:UNUSED_PAD src0_sel:WORD_1
	v_cvt_f32_f16_e32 v190, v132
	v_cvt_f32_f16_sdwa v191, v132 dst_sel:DWORD dst_unused:UNUSED_PAD src0_sel:WORD_1
	v_cvt_f32_f16_e32 v192, v133
	v_cvt_f32_f16_sdwa v193, v133 dst_sel:DWORD dst_unused:UNUSED_PAD src0_sel:WORD_1
	v_pk_fma_f32 v[62:63], v[62:63], 0.5, v[186:187] op_sel_hi:[1,0,1]
	v_pk_fma_f32 v[64:65], v[64:65], 0.5, v[188:189] op_sel_hi:[1,0,1]
	v_pk_fma_f32 v[58:59], v[58:59], 0.5, v[190:191] op_sel_hi:[1,0,1]
	v_pk_fma_f32 v[60:61], v[60:61], 0.5, v[192:193] op_sel_hi:[1,0,1]
	v_cvt_pk_f16_f32 v61, v60, v61
	v_cvt_pk_f16_f32 v60, v58, v59
	v_cvt_pk_f16_f32 v59, v64, v65
	v_cvt_pk_f16_f32 v58, v62, v63
	global_store_dwordx4 v[200:201], v[58:61], off
	s_waitcnt vmcnt(14)
	v_cvt_f32_f16_e32 v186, v134
	v_cvt_f32_f16_sdwa v187, v134 dst_sel:DWORD dst_unused:UNUSED_PAD src0_sel:WORD_1
	v_cvt_f32_f16_e32 v188, v135
	v_cvt_f32_f16_sdwa v189, v135 dst_sel:DWORD dst_unused:UNUSED_PAD src0_sel:WORD_1
	v_cvt_f32_f16_e32 v190, v136
	v_cvt_f32_f16_sdwa v191, v136 dst_sel:DWORD dst_unused:UNUSED_PAD src0_sel:WORD_1
	v_cvt_f32_f16_e32 v192, v137
	v_cvt_f32_f16_sdwa v193, v137 dst_sel:DWORD dst_unused:UNUSED_PAD src0_sel:WORD_1
	v_pk_fma_f32 v[54:55], v[54:55], 0.5, v[186:187] op_sel_hi:[1,0,1]
	v_pk_fma_f32 v[56:57], v[56:57], 0.5, v[188:189] op_sel_hi:[1,0,1]
	v_pk_fma_f32 v[46:47], v[46:47], 0.5, v[190:191] op_sel_hi:[1,0,1]
	v_pk_fma_f32 v[48:49], v[48:49], 0.5, v[192:193] op_sel_hi:[1,0,1]
	v_cvt_pk_f16_f32 v49, v48, v49
	v_cvt_pk_f16_f32 v48, v46, v47
	v_cvt_pk_f16_f32 v47, v56, v57
	v_cvt_pk_f16_f32 v46, v54, v55
	global_store_dwordx4 v[200:201], v[46:49], off offset:256
	s_waitcnt vmcnt(13)
	v_cvt_f32_f16_e32 v186, v138
	v_cvt_f32_f16_sdwa v187, v138 dst_sel:DWORD dst_unused:UNUSED_PAD src0_sel:WORD_1
	v_cvt_f32_f16_e32 v188, v139
	v_cvt_f32_f16_sdwa v189, v139 dst_sel:DWORD dst_unused:UNUSED_PAD src0_sel:WORD_1
	v_cvt_f32_f16_e32 v190, v140
	v_cvt_f32_f16_sdwa v191, v140 dst_sel:DWORD dst_unused:UNUSED_PAD src0_sel:WORD_1
	v_cvt_f32_f16_e32 v192, v141
	v_cvt_f32_f16_sdwa v193, v141 dst_sel:DWORD dst_unused:UNUSED_PAD src0_sel:WORD_1
	v_pk_fma_f32 v[50:51], v[50:51], 0.5, v[186:187] op_sel_hi:[1,0,1]
	v_pk_fma_f32 v[52:53], v[52:53], 0.5, v[188:189] op_sel_hi:[1,0,1]
	v_pk_fma_f32 v[42:43], v[42:43], 0.5, v[190:191] op_sel_hi:[1,0,1]
	v_pk_fma_f32 v[44:45], v[44:45], 0.5, v[192:193] op_sel_hi:[1,0,1]
	v_cvt_pk_f16_f32 v45, v44, v45
	v_cvt_pk_f16_f32 v44, v42, v43
	v_cvt_pk_f16_f32 v43, v52, v53
	v_cvt_pk_f16_f32 v42, v50, v51
	global_store_dwordx4 v[202:203], v[42:45], off
	s_waitcnt vmcnt(12)
	v_cvt_f32_f16_e32 v186, v142
	v_cvt_f32_f16_sdwa v187, v142 dst_sel:DWORD dst_unused:UNUSED_PAD src0_sel:WORD_1
	v_cvt_f32_f16_e32 v188, v143
	v_cvt_f32_f16_sdwa v189, v143 dst_sel:DWORD dst_unused:UNUSED_PAD src0_sel:WORD_1
	v_cvt_f32_f16_e32 v190, v144
	v_cvt_f32_f16_sdwa v191, v144 dst_sel:DWORD dst_unused:UNUSED_PAD src0_sel:WORD_1
	v_cvt_f32_f16_e32 v192, v145
	v_cvt_f32_f16_sdwa v193, v145 dst_sel:DWORD dst_unused:UNUSED_PAD src0_sel:WORD_1
	v_pk_fma_f32 v[30:31], v[30:31], 0.5, v[186:187] op_sel_hi:[1,0,1]
	v_pk_fma_f32 v[32:33], v[32:33], 0.5, v[188:189] op_sel_hi:[1,0,1]
	v_pk_fma_f32 v[26:27], v[26:27], 0.5, v[190:191] op_sel_hi:[1,0,1]
	v_pk_fma_f32 v[28:29], v[28:29], 0.5, v[192:193] op_sel_hi:[1,0,1]
	v_cvt_pk_f16_f32 v29, v28, v29
	v_cvt_pk_f16_f32 v28, v26, v27
	v_cvt_pk_f16_f32 v27, v32, v33
	v_cvt_pk_f16_f32 v26, v30, v31
	global_store_dwordx4 v[202:203], v[26:29], off offset:256
	s_waitcnt vmcnt(11)
	v_cvt_f32_f16_e32 v186, v162
	v_cvt_f32_f16_sdwa v187, v162 dst_sel:DWORD dst_unused:UNUSED_PAD src0_sel:WORD_1
	v_cvt_f32_f16_e32 v188, v163
	v_cvt_f32_f16_sdwa v189, v163 dst_sel:DWORD dst_unused:UNUSED_PAD src0_sel:WORD_1
	v_cvt_f32_f16_e32 v190, v164
	v_cvt_f32_f16_sdwa v191, v164 dst_sel:DWORD dst_unused:UNUSED_PAD src0_sel:WORD_1
	v_cvt_f32_f16_e32 v192, v165
	v_cvt_f32_f16_sdwa v193, v165 dst_sel:DWORD dst_unused:UNUSED_PAD src0_sel:WORD_1
	v_pk_fma_f32 v[38:39], v[38:39], 0.5, v[186:187] op_sel_hi:[1,0,1]
	v_pk_fma_f32 v[40:41], v[40:41], 0.5, v[188:189] op_sel_hi:[1,0,1]
	v_pk_fma_f32 v[34:35], v[34:35], 0.5, v[190:191] op_sel_hi:[1,0,1]
	v_pk_fma_f32 v[36:37], v[36:37], 0.5, v[192:193] op_sel_hi:[1,0,1]
	v_cvt_pk_f16_f32 v37, v36, v37
	v_cvt_pk_f16_f32 v36, v34, v35
	v_cvt_pk_f16_f32 v35, v40, v41
	v_cvt_pk_f16_f32 v34, v38, v39
	global_store_dwordx4 v[204:205], v[34:37], off
	s_waitcnt vmcnt(10)
	v_cvt_f32_f16_e32 v186, v166
	v_cvt_f32_f16_sdwa v187, v166 dst_sel:DWORD dst_unused:UNUSED_PAD src0_sel:WORD_1
	v_cvt_f32_f16_e32 v188, v167
	v_cvt_f32_f16_sdwa v189, v167 dst_sel:DWORD dst_unused:UNUSED_PAD src0_sel:WORD_1
	v_cvt_f32_f16_e32 v190, v168
	v_cvt_f32_f16_sdwa v191, v168 dst_sel:DWORD dst_unused:UNUSED_PAD src0_sel:WORD_1
	v_cvt_f32_f16_e32 v192, v169
	v_cvt_f32_f16_sdwa v193, v169 dst_sel:DWORD dst_unused:UNUSED_PAD src0_sel:WORD_1
	v_pk_fma_f32 v[22:23], v[22:23], 0.5, v[186:187] op_sel_hi:[1,0,1]
	v_pk_fma_f32 v[24:25], v[24:25], 0.5, v[188:189] op_sel_hi:[1,0,1]
	v_pk_fma_f32 v[18:19], v[18:19], 0.5, v[190:191] op_sel_hi:[1,0,1]
	v_pk_fma_f32 v[20:21], v[20:21], 0.5, v[192:193] op_sel_hi:[1,0,1]
	v_cvt_pk_f16_f32 v21, v20, v21
	v_cvt_pk_f16_f32 v20, v18, v19
	v_cvt_pk_f16_f32 v19, v24, v25
	v_cvt_pk_f16_f32 v18, v22, v23
	global_store_dwordx4 v[204:205], v[18:21], off offset:256
	s_waitcnt vmcnt(9)
	v_cvt_f32_f16_e32 v186, v170
	v_cvt_f32_f16_sdwa v187, v170 dst_sel:DWORD dst_unused:UNUSED_PAD src0_sel:WORD_1
	v_cvt_f32_f16_e32 v188, v171
	v_cvt_f32_f16_sdwa v189, v171 dst_sel:DWORD dst_unused:UNUSED_PAD src0_sel:WORD_1
	v_cvt_f32_f16_e32 v190, v172
	v_cvt_f32_f16_sdwa v191, v172 dst_sel:DWORD dst_unused:UNUSED_PAD src0_sel:WORD_1
	v_cvt_f32_f16_e32 v192, v173
	v_cvt_f32_f16_sdwa v193, v173 dst_sel:DWORD dst_unused:UNUSED_PAD src0_sel:WORD_1
	v_pk_fma_f32 v[14:15], v[14:15], 0.5, v[186:187] op_sel_hi:[1,0,1]
	v_pk_fma_f32 v[16:17], v[16:17], 0.5, v[188:189] op_sel_hi:[1,0,1]
	v_pk_fma_f32 v[10:11], v[10:11], 0.5, v[190:191] op_sel_hi:[1,0,1]
	v_pk_fma_f32 v[12:13], v[12:13], 0.5, v[192:193] op_sel_hi:[1,0,1]
	v_cvt_pk_f16_f32 v13, v12, v13
	v_cvt_pk_f16_f32 v12, v10, v11
	v_cvt_pk_f16_f32 v11, v16, v17
	v_cvt_pk_f16_f32 v10, v14, v15
	global_store_dwordx4 v[206:207], v[10:13], off
	s_waitcnt vmcnt(8)
	v_cvt_f32_f16_e32 v186, v182
	v_cvt_f32_f16_sdwa v187, v182 dst_sel:DWORD dst_unused:UNUSED_PAD src0_sel:WORD_1
	v_cvt_f32_f16_e32 v188, v183
	v_cvt_f32_f16_sdwa v189, v183 dst_sel:DWORD dst_unused:UNUSED_PAD src0_sel:WORD_1
	v_cvt_f32_f16_e32 v190, v184
	v_cvt_f32_f16_sdwa v191, v184 dst_sel:DWORD dst_unused:UNUSED_PAD src0_sel:WORD_1
	v_cvt_f32_f16_e32 v192, v185
	v_cvt_f32_f16_sdwa v193, v185 dst_sel:DWORD dst_unused:UNUSED_PAD src0_sel:WORD_1
	v_pk_fma_f32 v[6:7], v[6:7], 0.5, v[186:187] op_sel_hi:[1,0,1]
	v_pk_fma_f32 v[8:9], v[8:9], 0.5, v[188:189] op_sel_hi:[1,0,1]
	v_pk_fma_f32 v[2:3], v[2:3], 0.5, v[190:191] op_sel_hi:[1,0,1]
	v_pk_fma_f32 v[4:5], v[4:5], 0.5, v[192:193] op_sel_hi:[1,0,1]
	v_cvt_pk_f16_f32 v5, v4, v5
	v_cvt_pk_f16_f32 v4, v2, v3
	v_cvt_pk_f16_f32 v3, v8, v9
	v_cvt_pk_f16_f32 v2, v6, v7
	global_store_dwordx4 v[206:207], v[2:5], off offset:256
	s_and_b64 vcc, exec, s[2:3]
	s_mov_b64 s[0:1], -1
	s_cbranch_vccnz .LBB0_2077
	s_andn2_b64 vcc, exec, s[8:9]
	s_cbranch_vccnz .LBB0_2076
	s_barrier
	s_branch .LBB0_2076

.LBB0_2941:
	v_lshl_or_b32 v130, s61, 8, v173
	v_lshl_add_u32 v158, s44, 8, v1
	v_ashrrev_i32_e32 v131, 31, v130
	v_lshlrev_b64 v[160:161], 1, v[130:131]
	v_or_b32_e32 v130, 16, v158
	v_ashrrev_i32_e32 v159, 31, v158
	v_ashrrev_i32_e32 v131, 31, v130
	v_lshlrev_b64 v[132:133], 12, v[158:159]
	v_lshlrev_b64 v[130:131], 12, v[130:131]
	v_lshl_add_u64 v[132:133], s[64:65], 0, v[132:133]
	v_lshl_add_u64 v[130:131], s[64:65], 0, v[130:131]
	v_lshl_add_u64 v[170:171], v[132:133], 0, v[160:161]
	v_lshl_add_u64 v[168:169], v[130:131], 0, v[160:161]
	v_mov_b32_e32 v209, 0
	v_mov_b32_e32 v208, 0x10000
	v_lshl_add_u64 v[194:195], v[208:209], 0, v[170:171]
	v_mov_b32_e32 v208, 0x20000
	v_lshl_add_u64 v[196:197], v[208:209], 0, v[170:171]
	v_mov_b32_e32 v208, 0x30000
	v_lshl_add_u64 v[198:199], v[208:209], 0, v[170:171]
	v_mov_b32_e32 v208, 0x80000
	v_lshl_add_u64 v[200:201], v[208:209], 0, v[170:171]
	v_mov_b32_e32 v208, 0x90000
	v_lshl_add_u64 v[202:203], v[208:209], 0, v[170:171]
	v_mov_b32_e32 v208, 0xa0000
	v_lshl_add_u64 v[204:205], v[208:209], 0, v[170:171]
	v_mov_b32_e32 v208, 0xb0000
	v_lshl_add_u64 v[206:207], v[208:209], 0, v[170:171]
	global_load_dwordx4 v[130:133], v[170:171], off
	global_load_dwordx4 v[134:137], v[170:171], off offset:256
	global_load_dwordx4 v[138:141], v[194:195], off
	global_load_dwordx4 v[158:161], v[194:195], off offset:256
	global_load_dwordx4 v[162:165], v[196:197], off
	global_load_dwordx4 v[166:169], v[196:197], off offset:256
	global_load_dwordx4 v[178:181], v[198:199], off
	global_load_dwordx4 v[182:185], v[198:199], off offset:256
	s_waitcnt vmcnt(7)
	v_cvt_f32_f16_e32 v186, v130
	v_cvt_f32_f16_sdwa v187, v130 dst_sel:DWORD dst_unused:UNUSED_PAD src0_sel:WORD_1
	v_cvt_f32_f16_e32 v188, v131
	v_cvt_f32_f16_sdwa v189, v131 dst_sel:DWORD dst_unused:UNUSED_PAD src0_sel:WORD_1
	v_cvt_f32_f16_e32 v190, v132
	v_cvt_f32_f16_sdwa v191, v132 dst_sel:DWORD dst_unused:UNUSED_PAD src0_sel:WORD_1
	v_cvt_f32_f16_e32 v192, v133
	v_cvt_f32_f16_sdwa v193, v133 dst_sel:DWORD dst_unused:UNUSED_PAD src0_sel:WORD_1
	global_load_dwordx4 v[130:133], v[200:201], off
	v_pk_add_f32 v[126:127], v[186:187], v[126:127]
	v_pk_add_f32 v[128:129], v[188:189], v[128:129]
	v_pk_add_f32 v[122:123], v[190:191], v[122:123]
	v_pk_add_f32 v[124:125], v[192:193], v[124:125]
	v_cvt_pk_f16_f32 v125, v124, v125
	v_cvt_pk_f16_f32 v124, v122, v123
	v_cvt_pk_f16_f32 v123, v128, v129
	v_cvt_pk_f16_f32 v122, v126, v127
	global_store_dwordx4 v[170:171], v[122:125], off
	s_waitcnt vmcnt(8)
	v_cvt_f32_f16_e32 v186, v134
	v_cvt_f32_f16_sdwa v187, v134 dst_sel:DWORD dst_unused:UNUSED_PAD src0_sel:WORD_1
	v_cvt_f32_f16_e32 v188, v135
	v_cvt_f32_f16_sdwa v189, v135 dst_sel:DWORD dst_unused:UNUSED_PAD src0_sel:WORD_1
	v_cvt_f32_f16_e32 v190, v136
	v_cvt_f32_f16_sdwa v191, v136 dst_sel:DWORD dst_unused:UNUSED_PAD src0_sel:WORD_1
	v_cvt_f32_f16_e32 v192, v137
	v_cvt_f32_f16_sdwa v193, v137 dst_sel:DWORD dst_unused:UNUSED_PAD src0_sel:WORD_1
	global_load_dwordx4 v[134:137], v[200:201], off offset:256
	v_pk_add_f32 v[118:119], v[186:187], v[118:119]
	v_pk_add_f32 v[120:121], v[188:189], v[120:121]
	v_pk_add_f32 v[114:115], v[190:191], v[114:115]
	v_pk_add_f32 v[116:117], v[192:193], v[116:117]
	v_cvt_pk_f16_f32 v117, v116, v117
	v_cvt_pk_f16_f32 v116, v114, v115
	v_cvt_pk_f16_f32 v115, v120, v121
	v_cvt_pk_f16_f32 v114, v118, v119
	global_store_dwordx4 v[170:171], v[114:117], off offset:256
	s_waitcnt vmcnt(9)
	v_cvt_f32_f16_e32 v186, v138
	v_cvt_f32_f16_sdwa v187, v138 dst_sel:DWORD dst_unused:UNUSED_PAD src0_sel:WORD_1
	v_cvt_f32_f16_e32 v188, v139
	v_cvt_f32_f16_sdwa v189, v139 dst_sel:DWORD dst_unused:UNUSED_PAD src0_sel:WORD_1
	v_cvt_f32_f16_e32 v190, v140
	v_cvt_f32_f16_sdwa v191, v140 dst_sel:DWORD dst_unused:UNUSED_PAD src0_sel:WORD_1
	v_cvt_f32_f16_e32 v192, v141
	v_cvt_f32_f16_sdwa v193, v141 dst_sel:DWORD dst_unused:UNUSED_PAD src0_sel:WORD_1
	global_load_dwordx4 v[138:141], v[202:203], off
	v_pk_add_f32 v[110:111], v[186:187], v[110:111]
	v_pk_add_f32 v[112:113], v[188:189], v[112:113]
	v_pk_add_f32 v[106:107], v[190:191], v[106:107]
	v_pk_add_f32 v[108:109], v[192:193], v[108:109]
	v_cvt_pk_f16_f32 v109, v108, v109
	v_cvt_pk_f16_f32 v108, v106, v107
	v_cvt_pk_f16_f32 v107, v112, v113
	v_cvt_pk_f16_f32 v106, v110, v111
	global_store_dwordx4 v[194:195], v[106:109], off
	s_waitcnt vmcnt(10)
	v_cvt_f32_f16_e32 v186, v158
	v_cvt_f32_f16_sdwa v187, v158 dst_sel:DWORD dst_unused:UNUSED_PAD src0_sel:WORD_1
	v_cvt_f32_f16_e32 v188, v159
	v_cvt_f32_f16_sdwa v189, v159 dst_sel:DWORD dst_unused:UNUSED_PAD src0_sel:WORD_1
	v_cvt_f32_f16_e32 v190, v160
	v_cvt_f32_f16_sdwa v191, v160 dst_sel:DWORD dst_unused:UNUSED_PAD src0_sel:WORD_1
	v_cvt_f32_f16_e32 v192, v161
	v_cvt_f32_f16_sdwa v193, v161 dst_sel:DWORD dst_unused:UNUSED_PAD src0_sel:WORD_1
	global_load_dwordx4 v[158:161], v[202:203], off offset:256
	v_pk_add_f32 v[102:103], v[186:187], v[102:103]
	v_pk_add_f32 v[104:105], v[188:189], v[104:105]
	v_pk_add_f32 v[98:99], v[190:191], v[98:99]
	v_pk_add_f32 v[100:101], v[192:193], v[100:101]
	v_cvt_pk_f16_f32 v101, v100, v101
	v_cvt_pk_f16_f32 v100, v98, v99
	v_cvt_pk_f16_f32 v99, v104, v105
	v_cvt_pk_f16_f32 v98, v102, v103
	global_store_dwordx4 v[194:195], v[98:101], off offset:256
	s_waitcnt vmcnt(11)
	v_cvt_f32_f16_e32 v186, v162
	v_cvt_f32_f16_sdwa v187, v162 dst_sel:DWORD dst_unused:UNUSED_PAD src0_sel:WORD_1
	v_cvt_f32_f16_e32 v188, v163
	v_cvt_f32_f16_sdwa v189, v163 dst_sel:DWORD dst_unused:UNUSED_PAD src0_sel:WORD_1
	v_cvt_f32_f16_e32 v190, v164
	v_cvt_f32_f16_sdwa v191, v164 dst_sel:DWORD dst_unused:UNUSED_PAD src0_sel:WORD_1
	v_cvt_f32_f16_e32 v192, v165
	v_cvt_f32_f16_sdwa v193, v165 dst_sel:DWORD dst_unused:UNUSED_PAD src0_sel:WORD_1
	global_load_dwordx4 v[162:165], v[204:205], off
	v_pk_add_f32 v[94:95], v[186:187], v[94:95]
	v_pk_add_f32 v[96:97], v[188:189], v[96:97]
	v_pk_add_f32 v[90:91], v[190:191], v[90:91]
	v_pk_add_f32 v[92:93], v[192:193], v[92:93]
	v_cvt_pk_f16_f32 v93, v92, v93
	v_cvt_pk_f16_f32 v92, v90, v91
	v_cvt_pk_f16_f32 v91, v96, v97
	v_cvt_pk_f16_f32 v90, v94, v95
	global_store_dwordx4 v[196:197], v[90:93], off
	s_waitcnt vmcnt(12)
	v_cvt_f32_f16_e32 v186, v166
	v_cvt_f32_f16_sdwa v187, v166 dst_sel:DWORD dst_unused:UNUSED_PAD src0_sel:WORD_1
	v_cvt_f32_f16_e32 v188, v167
	v_cvt_f32_f16_sdwa v189, v167 dst_sel:DWORD dst_unused:UNUSED_PAD src0_sel:WORD_1
	v_cvt_f32_f16_e32 v190, v168
	v_cvt_f32_f16_sdwa v191, v168 dst_sel:DWORD dst_unused:UNUSED_PAD src0_sel:WORD_1
	v_cvt_f32_f16_e32 v192, v169
	v_cvt_f32_f16_sdwa v193, v169 dst_sel:DWORD dst_unused:UNUSED_PAD src0_sel:WORD_1
	global_load_dwordx4 v[166:169], v[204:205], off offset:256
	v_pk_add_f32 v[86:87], v[186:187], v[86:87]
	v_pk_add_f32 v[88:89], v[188:189], v[88:89]
	v_pk_add_f32 v[82:83], v[190:191], v[82:83]
	v_pk_add_f32 v[84:85], v[192:193], v[84:85]
	v_cvt_pk_f16_f32 v85, v84, v85
	v_cvt_pk_f16_f32 v84, v82, v83
	v_cvt_pk_f16_f32 v83, v88, v89
	v_cvt_pk_f16_f32 v82, v86, v87
	global_store_dwordx4 v[196:197], v[82:85], off offset:256
	s_waitcnt vmcnt(13)
	v_cvt_f32_f16_e32 v186, v178
	v_cvt_f32_f16_sdwa v187, v178 dst_sel:DWORD dst_unused:UNUSED_PAD src0_sel:WORD_1
	v_cvt_f32_f16_e32 v188, v179
	v_cvt_f32_f16_sdwa v189, v179 dst_sel:DWORD dst_unused:UNUSED_PAD src0_sel:WORD_1
	v_cvt_f32_f16_e32 v190, v180
	v_cvt_f32_f16_sdwa v191, v180 dst_sel:DWORD dst_unused:UNUSED_PAD src0_sel:WORD_1
	v_cvt_f32_f16_e32 v192, v181
	v_cvt_f32_f16_sdwa v193, v181 dst_sel:DWORD dst_unused:UNUSED_PAD src0_sel:WORD_1
	global_load_dwordx4 v[178:181], v[206:207], off
	v_pk_add_f32 v[78:79], v[186:187], v[78:79]
	v_pk_add_f32 v[80:81], v[188:189], v[80:81]
	v_pk_add_f32 v[74:75], v[190:191], v[74:75]
	v_pk_add_f32 v[76:77], v[192:193], v[76:77]
	v_cvt_pk_f16_f32 v77, v76, v77
	v_cvt_pk_f16_f32 v76, v74, v75
	v_cvt_pk_f16_f32 v75, v80, v81
	v_cvt_pk_f16_f32 v74, v78, v79
	global_store_dwordx4 v[198:199], v[74:77], off
	s_waitcnt vmcnt(14)
	v_cvt_f32_f16_e32 v186, v182
	v_cvt_f32_f16_sdwa v187, v182 dst_sel:DWORD dst_unused:UNUSED_PAD src0_sel:WORD_1
	v_cvt_f32_f16_e32 v188, v183
	v_cvt_f32_f16_sdwa v189, v183 dst_sel:DWORD dst_unused:UNUSED_PAD src0_sel:WORD_1
	v_cvt_f32_f16_e32 v190, v184
	v_cvt_f32_f16_sdwa v191, v184 dst_sel:DWORD dst_unused:UNUSED_PAD src0_sel:WORD_1
	v_cvt_f32_f16_e32 v192, v185
	v_cvt_f32_f16_sdwa v193, v185 dst_sel:DWORD dst_unused:UNUSED_PAD src0_sel:WORD_1
	global_load_dwordx4 v[182:185], v[206:207], off offset:256
	v_pk_add_f32 v[70:71], v[186:187], v[70:71]
	v_pk_add_f32 v[72:73], v[188:189], v[72:73]
	v_pk_add_f32 v[66:67], v[190:191], v[66:67]
	v_pk_add_f32 v[68:69], v[192:193], v[68:69]
	v_cvt_pk_f16_f32 v69, v68, v69
	v_cvt_pk_f16_f32 v68, v66, v67
	v_cvt_pk_f16_f32 v67, v72, v73
	v_cvt_pk_f16_f32 v66, v70, v71
	global_store_dwordx4 v[198:199], v[66:69], off offset:256
	s_waitcnt vmcnt(15)
	v_cvt_f32_f16_e32 v186, v130
	v_cvt_f32_f16_sdwa v187, v130 dst_sel:DWORD dst_unused:UNUSED_PAD src0_sel:WORD_1
	v_cvt_f32_f16_e32 v188, v131
	v_cvt_f32_f16_sdwa v189, v131 dst_sel:DWORD dst_unused:UNUSED_PAD src0_sel:WORD_1
	v_cvt_f32_f16_e32 v190, v132
	v_cvt_f32_f16_sdwa v191, v132 dst_sel:DWORD dst_unused:UNUSED_PAD src0_sel:WORD_1
	v_cvt_f32_f16_e32 v192, v133
	v_cvt_f32_f16_sdwa v193, v133 dst_sel:DWORD dst_unused:UNUSED_PAD src0_sel:WORD_1
	v_pk_add_f32 v[62:63], v[186:187], v[62:63]
	v_pk_add_f32 v[64:65], v[188:189], v[64:65]
	v_pk_add_f32 v[58:59], v[190:191], v[58:59]
	v_pk_add_f32 v[60:61], v[192:193], v[60:61]
	v_cvt_pk_f16_f32 v61, v60, v61
	v_cvt_pk_f16_f32 v60, v58, v59
	v_cvt_pk_f16_f32 v59, v64, v65
	v_cvt_pk_f16_f32 v58, v62, v63
	global_store_dwordx4 v[200:201], v[58:61], off
	s_waitcnt vmcnt(14)
	v_cvt_f32_f16_e32 v186, v134
	v_cvt_f32_f16_sdwa v187, v134 dst_sel:DWORD dst_unused:UNUSED_PAD src0_sel:WORD_1
	v_cvt_f32_f16_e32 v188, v135
	v_cvt_f32_f16_sdwa v189, v135 dst_sel:DWORD dst_unused:UNUSED_PAD src0_sel:WORD_1
	v_cvt_f32_f16_e32 v190, v136
	v_cvt_f32_f16_sdwa v191, v136 dst_sel:DWORD dst_unused:UNUSED_PAD src0_sel:WORD_1
	v_cvt_f32_f16_e32 v192, v137
	v_cvt_f32_f16_sdwa v193, v137 dst_sel:DWORD dst_unused:UNUSED_PAD src0_sel:WORD_1
	v_pk_add_f32 v[54:55], v[186:187], v[54:55]
	v_pk_add_f32 v[56:57], v[188:189], v[56:57]
	v_pk_add_f32 v[46:47], v[190:191], v[46:47]
	v_pk_add_f32 v[48:49], v[192:193], v[48:49]
	v_cvt_pk_f16_f32 v49, v48, v49
	v_cvt_pk_f16_f32 v48, v46, v47
	v_cvt_pk_f16_f32 v47, v56, v57
	v_cvt_pk_f16_f32 v46, v54, v55
	global_store_dwordx4 v[200:201], v[46:49], off offset:256
	s_waitcnt vmcnt(13)
	v_cvt_f32_f16_e32 v186, v138
	v_cvt_f32_f16_sdwa v187, v138 dst_sel:DWORD dst_unused:UNUSED_PAD src0_sel:WORD_1
	v_cvt_f32_f16_e32 v188, v139
	v_cvt_f32_f16_sdwa v189, v139 dst_sel:DWORD dst_unused:UNUSED_PAD src0_sel:WORD_1
	v_cvt_f32_f16_e32 v190, v140
	v_cvt_f32_f16_sdwa v191, v140 dst_sel:DWORD dst_unused:UNUSED_PAD src0_sel:WORD_1
	v_cvt_f32_f16_e32 v192, v141
	v_cvt_f32_f16_sdwa v193, v141 dst_sel:DWORD dst_unused:UNUSED_PAD src0_sel:WORD_1
	v_pk_add_f32 v[50:51], v[186:187], v[50:51]
	v_pk_add_f32 v[52:53], v[188:189], v[52:53]
	v_pk_add_f32 v[42:43], v[190:191], v[42:43]
	v_pk_add_f32 v[44:45], v[192:193], v[44:45]
	v_cvt_pk_f16_f32 v45, v44, v45
	v_cvt_pk_f16_f32 v44, v42, v43
	v_cvt_pk_f16_f32 v43, v52, v53
	v_cvt_pk_f16_f32 v42, v50, v51
	global_store_dwordx4 v[202:203], v[42:45], off
	s_waitcnt vmcnt(12)
	v_cvt_f32_f16_e32 v186, v158
	v_cvt_f32_f16_sdwa v187, v158 dst_sel:DWORD dst_unused:UNUSED_PAD src0_sel:WORD_1
	v_cvt_f32_f16_e32 v188, v159
	v_cvt_f32_f16_sdwa v189, v159 dst_sel:DWORD dst_unused:UNUSED_PAD src0_sel:WORD_1
	v_cvt_f32_f16_e32 v190, v160
	v_cvt_f32_f16_sdwa v191, v160 dst_sel:DWORD dst_unused:UNUSED_PAD src0_sel:WORD_1
	v_cvt_f32_f16_e32 v192, v161
	v_cvt_f32_f16_sdwa v193, v161 dst_sel:DWORD dst_unused:UNUSED_PAD src0_sel:WORD_1
	v_pk_add_f32 v[30:31], v[186:187], v[30:31]
	v_pk_add_f32 v[32:33], v[188:189], v[32:33]
	v_pk_add_f32 v[26:27], v[190:191], v[26:27]
	v_pk_add_f32 v[28:29], v[192:193], v[28:29]
	v_cvt_pk_f16_f32 v29, v28, v29
	v_cvt_pk_f16_f32 v28, v26, v27
	v_cvt_pk_f16_f32 v27, v32, v33
	v_cvt_pk_f16_f32 v26, v30, v31
	global_store_dwordx4 v[202:203], v[26:29], off offset:256
	s_waitcnt vmcnt(11)
	v_cvt_f32_f16_e32 v186, v162
	v_cvt_f32_f16_sdwa v187, v162 dst_sel:DWORD dst_unused:UNUSED_PAD src0_sel:WORD_1
	v_cvt_f32_f16_e32 v188, v163
	v_cvt_f32_f16_sdwa v189, v163 dst_sel:DWORD dst_unused:UNUSED_PAD src0_sel:WORD_1
	v_cvt_f32_f16_e32 v190, v164
	v_cvt_f32_f16_sdwa v191, v164 dst_sel:DWORD dst_unused:UNUSED_PAD src0_sel:WORD_1
	v_cvt_f32_f16_e32 v192, v165
	v_cvt_f32_f16_sdwa v193, v165 dst_sel:DWORD dst_unused:UNUSED_PAD src0_sel:WORD_1
	v_pk_add_f32 v[38:39], v[186:187], v[38:39]
	v_pk_add_f32 v[40:41], v[188:189], v[40:41]
	v_pk_add_f32 v[34:35], v[190:191], v[34:35]
	v_pk_add_f32 v[36:37], v[192:193], v[36:37]
	v_cvt_pk_f16_f32 v37, v36, v37
	v_cvt_pk_f16_f32 v36, v34, v35
	v_cvt_pk_f16_f32 v35, v40, v41
	v_cvt_pk_f16_f32 v34, v38, v39
	global_store_dwordx4 v[204:205], v[34:37], off
	s_waitcnt vmcnt(10)
	v_cvt_f32_f16_e32 v186, v166
	v_cvt_f32_f16_sdwa v187, v166 dst_sel:DWORD dst_unused:UNUSED_PAD src0_sel:WORD_1
	v_cvt_f32_f16_e32 v188, v167
	v_cvt_f32_f16_sdwa v189, v167 dst_sel:DWORD dst_unused:UNUSED_PAD src0_sel:WORD_1
	v_cvt_f32_f16_e32 v190, v168
	v_cvt_f32_f16_sdwa v191, v168 dst_sel:DWORD dst_unused:UNUSED_PAD src0_sel:WORD_1
	v_cvt_f32_f16_e32 v192, v169
	v_cvt_f32_f16_sdwa v193, v169 dst_sel:DWORD dst_unused:UNUSED_PAD src0_sel:WORD_1
	v_pk_add_f32 v[22:23], v[186:187], v[22:23]
	v_pk_add_f32 v[24:25], v[188:189], v[24:25]
	v_pk_add_f32 v[18:19], v[190:191], v[18:19]
	v_pk_add_f32 v[20:21], v[192:193], v[20:21]
	v_cvt_pk_f16_f32 v21, v20, v21
	v_cvt_pk_f16_f32 v20, v18, v19
	v_cvt_pk_f16_f32 v19, v24, v25
	v_cvt_pk_f16_f32 v18, v22, v23
	global_store_dwordx4 v[204:205], v[18:21], off offset:256
	s_waitcnt vmcnt(9)
	v_cvt_f32_f16_e32 v186, v178
	v_cvt_f32_f16_sdwa v187, v178 dst_sel:DWORD dst_unused:UNUSED_PAD src0_sel:WORD_1
	v_cvt_f32_f16_e32 v188, v179
	v_cvt_f32_f16_sdwa v189, v179 dst_sel:DWORD dst_unused:UNUSED_PAD src0_sel:WORD_1
	v_cvt_f32_f16_e32 v190, v180
	v_cvt_f32_f16_sdwa v191, v180 dst_sel:DWORD dst_unused:UNUSED_PAD src0_sel:WORD_1
	v_cvt_f32_f16_e32 v192, v181
	v_cvt_f32_f16_sdwa v193, v181 dst_sel:DWORD dst_unused:UNUSED_PAD src0_sel:WORD_1
	v_pk_add_f32 v[14:15], v[186:187], v[14:15]
	v_pk_add_f32 v[16:17], v[188:189], v[16:17]
	v_pk_add_f32 v[10:11], v[190:191], v[10:11]
	v_pk_add_f32 v[12:13], v[192:193], v[12:13]
	v_cvt_pk_f16_f32 v13, v12, v13
	v_cvt_pk_f16_f32 v12, v10, v11
	v_cvt_pk_f16_f32 v11, v16, v17
	v_cvt_pk_f16_f32 v10, v14, v15
	global_store_dwordx4 v[206:207], v[10:13], off
	s_waitcnt vmcnt(8)
	v_cvt_f32_f16_e32 v186, v182
	v_cvt_f32_f16_sdwa v187, v182 dst_sel:DWORD dst_unused:UNUSED_PAD src0_sel:WORD_1
	v_cvt_f32_f16_e32 v188, v183
	v_cvt_f32_f16_sdwa v189, v183 dst_sel:DWORD dst_unused:UNUSED_PAD src0_sel:WORD_1
	v_cvt_f32_f16_e32 v190, v184
	v_cvt_f32_f16_sdwa v191, v184 dst_sel:DWORD dst_unused:UNUSED_PAD src0_sel:WORD_1
	v_cvt_f32_f16_e32 v192, v185
	v_cvt_f32_f16_sdwa v193, v185 dst_sel:DWORD dst_unused:UNUSED_PAD src0_sel:WORD_1
	v_pk_add_f32 v[6:7], v[186:187], v[6:7]
	v_pk_add_f32 v[8:9], v[188:189], v[8:9]
	v_pk_add_f32 v[2:3], v[190:191], v[2:3]
	v_pk_add_f32 v[4:5], v[192:193], v[4:5]
	v_cvt_pk_f16_f32 v5, v4, v5
	v_cvt_pk_f16_f32 v4, v2, v3
	v_cvt_pk_f16_f32 v3, v8, v9
	v_cvt_pk_f16_f32 v2, v6, v7
	global_store_dwordx4 v[206:207], v[2:5], off offset:256
	s_mov_b64 s[0:1], -1
	s_andn2_b64 vcc, exec, s[2:3]
	s_cbranch_vccnz .LBB0_2930
	s_andn2_b64 vcc, exec, s[8:9]
	s_cbranch_vccnz .LBB0_2929
	s_barrier
	s_branch .LBB0_2929

.LBB0_3183:
	v_lshl_or_b32 v130, s59, 8, v173
	v_lshl_add_u32 v158, s58, 8, v1
	v_ashrrev_i32_e32 v131, 31, v130
	v_lshlrev_b64 v[160:161], 1, v[130:131]
	v_or_b32_e32 v130, 16, v158
	v_ashrrev_i32_e32 v159, 31, v158
	v_ashrrev_i32_e32 v131, 31, v130
	v_lshlrev_b64 v[132:133], 12, v[158:159]
	v_lshlrev_b64 v[130:131], 12, v[130:131]
	v_lshl_add_u64 v[132:133], s[64:65], 0, v[132:133]
	v_lshl_add_u64 v[130:131], s[64:65], 0, v[130:131]
	v_lshl_add_u64 v[170:171], v[132:133], 0, v[160:161]
	v_lshl_add_u64 v[168:169], v[130:131], 0, v[160:161]
	v_mov_b32_e32 v209, 0
	v_mov_b32_e32 v208, 0x10000
	v_lshl_add_u64 v[194:195], v[208:209], 0, v[170:171]
	v_mov_b32_e32 v208, 0x20000
	v_lshl_add_u64 v[196:197], v[208:209], 0, v[170:171]
	v_mov_b32_e32 v208, 0x30000
	v_lshl_add_u64 v[198:199], v[208:209], 0, v[170:171]
	v_mov_b32_e32 v208, 0x80000
	v_lshl_add_u64 v[200:201], v[208:209], 0, v[170:171]
	v_mov_b32_e32 v208, 0x90000
	v_lshl_add_u64 v[202:203], v[208:209], 0, v[170:171]
	v_mov_b32_e32 v208, 0xa0000
	v_lshl_add_u64 v[204:205], v[208:209], 0, v[170:171]
	v_mov_b32_e32 v208, 0xb0000
	v_lshl_add_u64 v[206:207], v[208:209], 0, v[170:171]
	global_load_dwordx4 v[130:133], v[170:171], off
	global_load_dwordx4 v[134:137], v[170:171], off offset:256
	global_load_dwordx4 v[138:141], v[194:195], off
	global_load_dwordx4 v[158:161], v[194:195], off offset:256
	global_load_dwordx4 v[162:165], v[196:197], off
	global_load_dwordx4 v[166:169], v[196:197], off offset:256
	global_load_dwordx4 v[178:181], v[198:199], off
	global_load_dwordx4 v[182:185], v[198:199], off offset:256
	s_waitcnt vmcnt(7)
	v_cvt_f32_f16_e32 v186, v130
	v_cvt_f32_f16_sdwa v187, v130 dst_sel:DWORD dst_unused:UNUSED_PAD src0_sel:WORD_1
	v_cvt_f32_f16_e32 v188, v131
	v_cvt_f32_f16_sdwa v189, v131 dst_sel:DWORD dst_unused:UNUSED_PAD src0_sel:WORD_1
	v_cvt_f32_f16_e32 v190, v132
	v_cvt_f32_f16_sdwa v191, v132 dst_sel:DWORD dst_unused:UNUSED_PAD src0_sel:WORD_1
	v_cvt_f32_f16_e32 v192, v133
	v_cvt_f32_f16_sdwa v193, v133 dst_sel:DWORD dst_unused:UNUSED_PAD src0_sel:WORD_1
	global_load_dwordx4 v[130:133], v[200:201], off
	v_pk_fma_f32 v[126:127], v[126:127], 0.5, v[186:187] op_sel_hi:[1,0,1]
	v_pk_fma_f32 v[128:129], v[128:129], 0.5, v[188:189] op_sel_hi:[1,0,1]
	v_pk_fma_f32 v[122:123], v[122:123], 0.5, v[190:191] op_sel_hi:[1,0,1]
	v_pk_fma_f32 v[124:125], v[124:125], 0.5, v[192:193] op_sel_hi:[1,0,1]
	v_cvt_pk_f16_f32 v125, v124, v125
	v_cvt_pk_f16_f32 v124, v122, v123
	v_cvt_pk_f16_f32 v123, v128, v129
	v_cvt_pk_f16_f32 v122, v126, v127
	global_store_dwordx4 v[170:171], v[122:125], off
	s_waitcnt vmcnt(8)
	v_cvt_f32_f16_e32 v186, v134
	v_cvt_f32_f16_sdwa v187, v134 dst_sel:DWORD dst_unused:UNUSED_PAD src0_sel:WORD_1
	v_cvt_f32_f16_e32 v188, v135
	v_cvt_f32_f16_sdwa v189, v135 dst_sel:DWORD dst_unused:UNUSED_PAD src0_sel:WORD_1
	v_cvt_f32_f16_e32 v190, v136
	v_cvt_f32_f16_sdwa v191, v136 dst_sel:DWORD dst_unused:UNUSED_PAD src0_sel:WORD_1
	v_cvt_f32_f16_e32 v192, v137
	v_cvt_f32_f16_sdwa v193, v137 dst_sel:DWORD dst_unused:UNUSED_PAD src0_sel:WORD_1
	global_load_dwordx4 v[134:137], v[200:201], off offset:256
	v_pk_fma_f32 v[118:119], v[118:119], 0.5, v[186:187] op_sel_hi:[1,0,1]
	v_pk_fma_f32 v[120:121], v[120:121], 0.5, v[188:189] op_sel_hi:[1,0,1]
	v_pk_fma_f32 v[114:115], v[114:115], 0.5, v[190:191] op_sel_hi:[1,0,1]
	v_pk_fma_f32 v[116:117], v[116:117], 0.5, v[192:193] op_sel_hi:[1,0,1]
	v_cvt_pk_f16_f32 v117, v116, v117
	v_cvt_pk_f16_f32 v116, v114, v115
	v_cvt_pk_f16_f32 v115, v120, v121
	v_cvt_pk_f16_f32 v114, v118, v119
	global_store_dwordx4 v[170:171], v[114:117], off offset:256
	s_waitcnt vmcnt(9)
	v_cvt_f32_f16_e32 v186, v138
	v_cvt_f32_f16_sdwa v187, v138 dst_sel:DWORD dst_unused:UNUSED_PAD src0_sel:WORD_1
	v_cvt_f32_f16_e32 v188, v139
	v_cvt_f32_f16_sdwa v189, v139 dst_sel:DWORD dst_unused:UNUSED_PAD src0_sel:WORD_1
	v_cvt_f32_f16_e32 v190, v140
	v_cvt_f32_f16_sdwa v191, v140 dst_sel:DWORD dst_unused:UNUSED_PAD src0_sel:WORD_1
	v_cvt_f32_f16_e32 v192, v141
	v_cvt_f32_f16_sdwa v193, v141 dst_sel:DWORD dst_unused:UNUSED_PAD src0_sel:WORD_1
	global_load_dwordx4 v[138:141], v[202:203], off
	v_pk_fma_f32 v[110:111], v[110:111], 0.5, v[186:187] op_sel_hi:[1,0,1]
	v_pk_fma_f32 v[112:113], v[112:113], 0.5, v[188:189] op_sel_hi:[1,0,1]
	v_pk_fma_f32 v[106:107], v[106:107], 0.5, v[190:191] op_sel_hi:[1,0,1]
	v_pk_fma_f32 v[108:109], v[108:109], 0.5, v[192:193] op_sel_hi:[1,0,1]
	v_cvt_pk_f16_f32 v109, v108, v109
	v_cvt_pk_f16_f32 v108, v106, v107
	v_cvt_pk_f16_f32 v107, v112, v113
	v_cvt_pk_f16_f32 v106, v110, v111
	global_store_dwordx4 v[194:195], v[106:109], off
	s_waitcnt vmcnt(10)
	v_cvt_f32_f16_e32 v186, v158
	v_cvt_f32_f16_sdwa v187, v158 dst_sel:DWORD dst_unused:UNUSED_PAD src0_sel:WORD_1
	v_cvt_f32_f16_e32 v188, v159
	v_cvt_f32_f16_sdwa v189, v159 dst_sel:DWORD dst_unused:UNUSED_PAD src0_sel:WORD_1
	v_cvt_f32_f16_e32 v190, v160
	v_cvt_f32_f16_sdwa v191, v160 dst_sel:DWORD dst_unused:UNUSED_PAD src0_sel:WORD_1
	v_cvt_f32_f16_e32 v192, v161
	v_cvt_f32_f16_sdwa v193, v161 dst_sel:DWORD dst_unused:UNUSED_PAD src0_sel:WORD_1
	global_load_dwordx4 v[158:161], v[202:203], off offset:256
	v_pk_fma_f32 v[102:103], v[102:103], 0.5, v[186:187] op_sel_hi:[1,0,1]
	v_pk_fma_f32 v[104:105], v[104:105], 0.5, v[188:189] op_sel_hi:[1,0,1]
	v_pk_fma_f32 v[98:99], v[98:99], 0.5, v[190:191] op_sel_hi:[1,0,1]
	v_pk_fma_f32 v[100:101], v[100:101], 0.5, v[192:193] op_sel_hi:[1,0,1]
	v_cvt_pk_f16_f32 v101, v100, v101
	v_cvt_pk_f16_f32 v100, v98, v99
	v_cvt_pk_f16_f32 v99, v104, v105
	v_cvt_pk_f16_f32 v98, v102, v103
	global_store_dwordx4 v[194:195], v[98:101], off offset:256
	s_waitcnt vmcnt(11)
	v_cvt_f32_f16_e32 v186, v162
	v_cvt_f32_f16_sdwa v187, v162 dst_sel:DWORD dst_unused:UNUSED_PAD src0_sel:WORD_1
	v_cvt_f32_f16_e32 v188, v163
	v_cvt_f32_f16_sdwa v189, v163 dst_sel:DWORD dst_unused:UNUSED_PAD src0_sel:WORD_1
	v_cvt_f32_f16_e32 v190, v164
	v_cvt_f32_f16_sdwa v191, v164 dst_sel:DWORD dst_unused:UNUSED_PAD src0_sel:WORD_1
	v_cvt_f32_f16_e32 v192, v165
	v_cvt_f32_f16_sdwa v193, v165 dst_sel:DWORD dst_unused:UNUSED_PAD src0_sel:WORD_1
	global_load_dwordx4 v[162:165], v[204:205], off
	v_pk_fma_f32 v[94:95], v[94:95], 0.5, v[186:187] op_sel_hi:[1,0,1]
	v_pk_fma_f32 v[96:97], v[96:97], 0.5, v[188:189] op_sel_hi:[1,0,1]
	v_pk_fma_f32 v[90:91], v[90:91], 0.5, v[190:191] op_sel_hi:[1,0,1]
	v_pk_fma_f32 v[92:93], v[92:93], 0.5, v[192:193] op_sel_hi:[1,0,1]
	v_cvt_pk_f16_f32 v93, v92, v93
	v_cvt_pk_f16_f32 v92, v90, v91
	v_cvt_pk_f16_f32 v91, v96, v97
	v_cvt_pk_f16_f32 v90, v94, v95
	global_store_dwordx4 v[196:197], v[90:93], off
	s_waitcnt vmcnt(12)
	v_cvt_f32_f16_e32 v186, v166
	v_cvt_f32_f16_sdwa v187, v166 dst_sel:DWORD dst_unused:UNUSED_PAD src0_sel:WORD_1
	v_cvt_f32_f16_e32 v188, v167
	v_cvt_f32_f16_sdwa v189, v167 dst_sel:DWORD dst_unused:UNUSED_PAD src0_sel:WORD_1
	v_cvt_f32_f16_e32 v190, v168
	v_cvt_f32_f16_sdwa v191, v168 dst_sel:DWORD dst_unused:UNUSED_PAD src0_sel:WORD_1
	v_cvt_f32_f16_e32 v192, v169
	v_cvt_f32_f16_sdwa v193, v169 dst_sel:DWORD dst_unused:UNUSED_PAD src0_sel:WORD_1
	global_load_dwordx4 v[166:169], v[204:205], off offset:256
	v_pk_fma_f32 v[86:87], v[86:87], 0.5, v[186:187] op_sel_hi:[1,0,1]
	v_pk_fma_f32 v[88:89], v[88:89], 0.5, v[188:189] op_sel_hi:[1,0,1]
	v_pk_fma_f32 v[82:83], v[82:83], 0.5, v[190:191] op_sel_hi:[1,0,1]
	v_pk_fma_f32 v[84:85], v[84:85], 0.5, v[192:193] op_sel_hi:[1,0,1]
	v_cvt_pk_f16_f32 v85, v84, v85
	v_cvt_pk_f16_f32 v84, v82, v83
	v_cvt_pk_f16_f32 v83, v88, v89
	v_cvt_pk_f16_f32 v82, v86, v87
	global_store_dwordx4 v[196:197], v[82:85], off offset:256
	s_waitcnt vmcnt(13)
	v_cvt_f32_f16_e32 v186, v178
	v_cvt_f32_f16_sdwa v187, v178 dst_sel:DWORD dst_unused:UNUSED_PAD src0_sel:WORD_1
	v_cvt_f32_f16_e32 v188, v179
	v_cvt_f32_f16_sdwa v189, v179 dst_sel:DWORD dst_unused:UNUSED_PAD src0_sel:WORD_1
	v_cvt_f32_f16_e32 v190, v180
	v_cvt_f32_f16_sdwa v191, v180 dst_sel:DWORD dst_unused:UNUSED_PAD src0_sel:WORD_1
	v_cvt_f32_f16_e32 v192, v181
	v_cvt_f32_f16_sdwa v193, v181 dst_sel:DWORD dst_unused:UNUSED_PAD src0_sel:WORD_1
	global_load_dwordx4 v[178:181], v[206:207], off
	v_pk_fma_f32 v[78:79], v[78:79], 0.5, v[186:187] op_sel_hi:[1,0,1]
	v_pk_fma_f32 v[80:81], v[80:81], 0.5, v[188:189] op_sel_hi:[1,0,1]
	v_pk_fma_f32 v[74:75], v[74:75], 0.5, v[190:191] op_sel_hi:[1,0,1]
	v_pk_fma_f32 v[76:77], v[76:77], 0.5, v[192:193] op_sel_hi:[1,0,1]
	v_cvt_pk_f16_f32 v77, v76, v77
	v_cvt_pk_f16_f32 v76, v74, v75
	v_cvt_pk_f16_f32 v75, v80, v81
	v_cvt_pk_f16_f32 v74, v78, v79
	global_store_dwordx4 v[198:199], v[74:77], off
	s_waitcnt vmcnt(14)
	v_cvt_f32_f16_e32 v186, v182
	v_cvt_f32_f16_sdwa v187, v182 dst_sel:DWORD dst_unused:UNUSED_PAD src0_sel:WORD_1
	v_cvt_f32_f16_e32 v188, v183
	v_cvt_f32_f16_sdwa v189, v183 dst_sel:DWORD dst_unused:UNUSED_PAD src0_sel:WORD_1
	v_cvt_f32_f16_e32 v190, v184
	v_cvt_f32_f16_sdwa v191, v184 dst_sel:DWORD dst_unused:UNUSED_PAD src0_sel:WORD_1
	v_cvt_f32_f16_e32 v192, v185
	v_cvt_f32_f16_sdwa v193, v185 dst_sel:DWORD dst_unused:UNUSED_PAD src0_sel:WORD_1
	global_load_dwordx4 v[182:185], v[206:207], off offset:256
	v_pk_fma_f32 v[70:71], v[70:71], 0.5, v[186:187] op_sel_hi:[1,0,1]
	v_pk_fma_f32 v[72:73], v[72:73], 0.5, v[188:189] op_sel_hi:[1,0,1]
	v_pk_fma_f32 v[66:67], v[66:67], 0.5, v[190:191] op_sel_hi:[1,0,1]
	v_pk_fma_f32 v[68:69], v[68:69], 0.5, v[192:193] op_sel_hi:[1,0,1]
	v_cvt_pk_f16_f32 v69, v68, v69
	v_cvt_pk_f16_f32 v68, v66, v67
	v_cvt_pk_f16_f32 v67, v72, v73
	v_cvt_pk_f16_f32 v66, v70, v71
	global_store_dwordx4 v[198:199], v[66:69], off offset:256
	s_waitcnt vmcnt(15)
	v_cvt_f32_f16_e32 v186, v130
	v_cvt_f32_f16_sdwa v187, v130 dst_sel:DWORD dst_unused:UNUSED_PAD src0_sel:WORD_1
	v_cvt_f32_f16_e32 v188, v131
	v_cvt_f32_f16_sdwa v189, v131 dst_sel:DWORD dst_unused:UNUSED_PAD src0_sel:WORD_1
	v_cvt_f32_f16_e32 v190, v132
	v_cvt_f32_f16_sdwa v191, v132 dst_sel:DWORD dst_unused:UNUSED_PAD src0_sel:WORD_1
	v_cvt_f32_f16_e32 v192, v133
	v_cvt_f32_f16_sdwa v193, v133 dst_sel:DWORD dst_unused:UNUSED_PAD src0_sel:WORD_1
	v_pk_fma_f32 v[62:63], v[62:63], 0.5, v[186:187] op_sel_hi:[1,0,1]
	v_pk_fma_f32 v[64:65], v[64:65], 0.5, v[188:189] op_sel_hi:[1,0,1]
	v_pk_fma_f32 v[58:59], v[58:59], 0.5, v[190:191] op_sel_hi:[1,0,1]
	v_pk_fma_f32 v[60:61], v[60:61], 0.5, v[192:193] op_sel_hi:[1,0,1]
	v_cvt_pk_f16_f32 v61, v60, v61
	v_cvt_pk_f16_f32 v60, v58, v59
	v_cvt_pk_f16_f32 v59, v64, v65
	v_cvt_pk_f16_f32 v58, v62, v63
	global_store_dwordx4 v[200:201], v[58:61], off
	s_waitcnt vmcnt(14)
	v_cvt_f32_f16_e32 v186, v134
	v_cvt_f32_f16_sdwa v187, v134 dst_sel:DWORD dst_unused:UNUSED_PAD src0_sel:WORD_1
	v_cvt_f32_f16_e32 v188, v135
	v_cvt_f32_f16_sdwa v189, v135 dst_sel:DWORD dst_unused:UNUSED_PAD src0_sel:WORD_1
	v_cvt_f32_f16_e32 v190, v136
	v_cvt_f32_f16_sdwa v191, v136 dst_sel:DWORD dst_unused:UNUSED_PAD src0_sel:WORD_1
	v_cvt_f32_f16_e32 v192, v137
	v_cvt_f32_f16_sdwa v193, v137 dst_sel:DWORD dst_unused:UNUSED_PAD src0_sel:WORD_1
	v_pk_fma_f32 v[54:55], v[54:55], 0.5, v[186:187] op_sel_hi:[1,0,1]
	v_pk_fma_f32 v[56:57], v[56:57], 0.5, v[188:189] op_sel_hi:[1,0,1]
	v_pk_fma_f32 v[46:47], v[46:47], 0.5, v[190:191] op_sel_hi:[1,0,1]
	v_pk_fma_f32 v[48:49], v[48:49], 0.5, v[192:193] op_sel_hi:[1,0,1]
	v_cvt_pk_f16_f32 v49, v48, v49
	v_cvt_pk_f16_f32 v48, v46, v47
	v_cvt_pk_f16_f32 v47, v56, v57
	v_cvt_pk_f16_f32 v46, v54, v55
	global_store_dwordx4 v[200:201], v[46:49], off offset:256
	s_waitcnt vmcnt(13)
	v_cvt_f32_f16_e32 v186, v138
	v_cvt_f32_f16_sdwa v187, v138 dst_sel:DWORD dst_unused:UNUSED_PAD src0_sel:WORD_1
	v_cvt_f32_f16_e32 v188, v139
	v_cvt_f32_f16_sdwa v189, v139 dst_sel:DWORD dst_unused:UNUSED_PAD src0_sel:WORD_1
	v_cvt_f32_f16_e32 v190, v140
	v_cvt_f32_f16_sdwa v191, v140 dst_sel:DWORD dst_unused:UNUSED_PAD src0_sel:WORD_1
	v_cvt_f32_f16_e32 v192, v141
	v_cvt_f32_f16_sdwa v193, v141 dst_sel:DWORD dst_unused:UNUSED_PAD src0_sel:WORD_1
	v_pk_fma_f32 v[50:51], v[50:51], 0.5, v[186:187] op_sel_hi:[1,0,1]
	v_pk_fma_f32 v[52:53], v[52:53], 0.5, v[188:189] op_sel_hi:[1,0,1]
	v_pk_fma_f32 v[42:43], v[42:43], 0.5, v[190:191] op_sel_hi:[1,0,1]
	v_pk_fma_f32 v[44:45], v[44:45], 0.5, v[192:193] op_sel_hi:[1,0,1]
	v_cvt_pk_f16_f32 v45, v44, v45
	v_cvt_pk_f16_f32 v44, v42, v43
	v_cvt_pk_f16_f32 v43, v52, v53
	v_cvt_pk_f16_f32 v42, v50, v51
	global_store_dwordx4 v[202:203], v[42:45], off
	s_waitcnt vmcnt(12)
	v_cvt_f32_f16_e32 v186, v158
	v_cvt_f32_f16_sdwa v187, v158 dst_sel:DWORD dst_unused:UNUSED_PAD src0_sel:WORD_1
	v_cvt_f32_f16_e32 v188, v159
	v_cvt_f32_f16_sdwa v189, v159 dst_sel:DWORD dst_unused:UNUSED_PAD src0_sel:WORD_1
	v_cvt_f32_f16_e32 v190, v160
	v_cvt_f32_f16_sdwa v191, v160 dst_sel:DWORD dst_unused:UNUSED_PAD src0_sel:WORD_1
	v_cvt_f32_f16_e32 v192, v161
	v_cvt_f32_f16_sdwa v193, v161 dst_sel:DWORD dst_unused:UNUSED_PAD src0_sel:WORD_1
	v_pk_fma_f32 v[30:31], v[30:31], 0.5, v[186:187] op_sel_hi:[1,0,1]
	v_pk_fma_f32 v[32:33], v[32:33], 0.5, v[188:189] op_sel_hi:[1,0,1]
	v_pk_fma_f32 v[26:27], v[26:27], 0.5, v[190:191] op_sel_hi:[1,0,1]
	v_pk_fma_f32 v[28:29], v[28:29], 0.5, v[192:193] op_sel_hi:[1,0,1]
	v_cvt_pk_f16_f32 v29, v28, v29
	v_cvt_pk_f16_f32 v28, v26, v27
	v_cvt_pk_f16_f32 v27, v32, v33
	v_cvt_pk_f16_f32 v26, v30, v31
	global_store_dwordx4 v[202:203], v[26:29], off offset:256
	s_waitcnt vmcnt(11)
	v_cvt_f32_f16_e32 v186, v162
	v_cvt_f32_f16_sdwa v187, v162 dst_sel:DWORD dst_unused:UNUSED_PAD src0_sel:WORD_1
	v_cvt_f32_f16_e32 v188, v163
	v_cvt_f32_f16_sdwa v189, v163 dst_sel:DWORD dst_unused:UNUSED_PAD src0_sel:WORD_1
	v_cvt_f32_f16_e32 v190, v164
	v_cvt_f32_f16_sdwa v191, v164 dst_sel:DWORD dst_unused:UNUSED_PAD src0_sel:WORD_1
	v_cvt_f32_f16_e32 v192, v165
	v_cvt_f32_f16_sdwa v193, v165 dst_sel:DWORD dst_unused:UNUSED_PAD src0_sel:WORD_1
	v_pk_fma_f32 v[38:39], v[38:39], 0.5, v[186:187] op_sel_hi:[1,0,1]
	v_pk_fma_f32 v[40:41], v[40:41], 0.5, v[188:189] op_sel_hi:[1,0,1]
	v_pk_fma_f32 v[34:35], v[34:35], 0.5, v[190:191] op_sel_hi:[1,0,1]
	v_pk_fma_f32 v[36:37], v[36:37], 0.5, v[192:193] op_sel_hi:[1,0,1]
	v_cvt_pk_f16_f32 v37, v36, v37
	v_cvt_pk_f16_f32 v36, v34, v35
	v_cvt_pk_f16_f32 v35, v40, v41
	v_cvt_pk_f16_f32 v34, v38, v39
	global_store_dwordx4 v[204:205], v[34:37], off
	s_waitcnt vmcnt(10)
	v_cvt_f32_f16_e32 v186, v166
	v_cvt_f32_f16_sdwa v187, v166 dst_sel:DWORD dst_unused:UNUSED_PAD src0_sel:WORD_1
	v_cvt_f32_f16_e32 v188, v167
	v_cvt_f32_f16_sdwa v189, v167 dst_sel:DWORD dst_unused:UNUSED_PAD src0_sel:WORD_1
	v_cvt_f32_f16_e32 v190, v168
	v_cvt_f32_f16_sdwa v191, v168 dst_sel:DWORD dst_unused:UNUSED_PAD src0_sel:WORD_1
	v_cvt_f32_f16_e32 v192, v169
	v_cvt_f32_f16_sdwa v193, v169 dst_sel:DWORD dst_unused:UNUSED_PAD src0_sel:WORD_1
	v_pk_fma_f32 v[22:23], v[22:23], 0.5, v[186:187] op_sel_hi:[1,0,1]
	v_pk_fma_f32 v[24:25], v[24:25], 0.5, v[188:189] op_sel_hi:[1,0,1]
	v_pk_fma_f32 v[18:19], v[18:19], 0.5, v[190:191] op_sel_hi:[1,0,1]
	v_pk_fma_f32 v[20:21], v[20:21], 0.5, v[192:193] op_sel_hi:[1,0,1]
	v_cvt_pk_f16_f32 v21, v20, v21
	v_cvt_pk_f16_f32 v20, v18, v19
	v_cvt_pk_f16_f32 v19, v24, v25
	v_cvt_pk_f16_f32 v18, v22, v23
	global_store_dwordx4 v[204:205], v[18:21], off offset:256
	s_waitcnt vmcnt(9)
	v_cvt_f32_f16_e32 v186, v178
	v_cvt_f32_f16_sdwa v187, v178 dst_sel:DWORD dst_unused:UNUSED_PAD src0_sel:WORD_1
	v_cvt_f32_f16_e32 v188, v179
	v_cvt_f32_f16_sdwa v189, v179 dst_sel:DWORD dst_unused:UNUSED_PAD src0_sel:WORD_1
	v_cvt_f32_f16_e32 v190, v180
	v_cvt_f32_f16_sdwa v191, v180 dst_sel:DWORD dst_unused:UNUSED_PAD src0_sel:WORD_1
	v_cvt_f32_f16_e32 v192, v181
	v_cvt_f32_f16_sdwa v193, v181 dst_sel:DWORD dst_unused:UNUSED_PAD src0_sel:WORD_1
	v_pk_fma_f32 v[14:15], v[14:15], 0.5, v[186:187] op_sel_hi:[1,0,1]
	v_pk_fma_f32 v[16:17], v[16:17], 0.5, v[188:189] op_sel_hi:[1,0,1]
	v_pk_fma_f32 v[10:11], v[10:11], 0.5, v[190:191] op_sel_hi:[1,0,1]
	v_pk_fma_f32 v[12:13], v[12:13], 0.5, v[192:193] op_sel_hi:[1,0,1]
	v_cvt_pk_f16_f32 v13, v12, v13
	v_cvt_pk_f16_f32 v12, v10, v11
	v_cvt_pk_f16_f32 v11, v16, v17
	v_cvt_pk_f16_f32 v10, v14, v15
	global_store_dwordx4 v[206:207], v[10:13], off
	s_waitcnt vmcnt(8)
	v_cvt_f32_f16_e32 v186, v182
	v_cvt_f32_f16_sdwa v187, v182 dst_sel:DWORD dst_unused:UNUSED_PAD src0_sel:WORD_1
	v_cvt_f32_f16_e32 v188, v183
	v_cvt_f32_f16_sdwa v189, v183 dst_sel:DWORD dst_unused:UNUSED_PAD src0_sel:WORD_1
	v_cvt_f32_f16_e32 v190, v184
	v_cvt_f32_f16_sdwa v191, v184 dst_sel:DWORD dst_unused:UNUSED_PAD src0_sel:WORD_1
	v_cvt_f32_f16_e32 v192, v185
	v_cvt_f32_f16_sdwa v193, v185 dst_sel:DWORD dst_unused:UNUSED_PAD src0_sel:WORD_1
	v_pk_fma_f32 v[6:7], v[6:7], 0.5, v[186:187] op_sel_hi:[1,0,1]
	v_pk_fma_f32 v[8:9], v[8:9], 0.5, v[188:189] op_sel_hi:[1,0,1]
	v_pk_fma_f32 v[2:3], v[2:3], 0.5, v[190:191] op_sel_hi:[1,0,1]
	v_pk_fma_f32 v[4:5], v[4:5], 0.5, v[192:193] op_sel_hi:[1,0,1]
	v_cvt_pk_f16_f32 v5, v4, v5
	v_cvt_pk_f16_f32 v4, v2, v3
	v_cvt_pk_f16_f32 v3, v8, v9
	v_cvt_pk_f16_f32 v2, v6, v7
	global_store_dwordx4 v[206:207], v[2:5], off offset:256
	s_mov_b64 s[0:1], -1
	s_and_b64 vcc, exec, s[2:3]
	s_cbranch_vccnz .LBB0_3168
	s_andn2_b64 vcc, exec, s[8:9]
	s_cbranch_vccnz .LBB0_3167
	s_barrier
	s_branch .LBB0_3167

.LBB0_3709:
	v_lshl_or_b32 v130, s57, 8, v173
	v_lshl_add_u32 v158, s40, 8, v1
	v_ashrrev_i32_e32 v131, 31, v130
	v_lshlrev_b64 v[160:161], 1, v[130:131]
	v_or_b32_e32 v130, 16, v158
	v_ashrrev_i32_e32 v159, 31, v158
	v_ashrrev_i32_e32 v131, 31, v130
	v_lshlrev_b64 v[132:133], 12, v[158:159]
	v_lshlrev_b64 v[130:131], 12, v[130:131]
	v_lshl_add_u64 v[132:133], s[64:65], 0, v[132:133]
	v_lshl_add_u64 v[130:131], s[64:65], 0, v[130:131]
	v_lshl_add_u64 v[170:171], v[132:133], 0, v[160:161]
	v_lshl_add_u64 v[168:169], v[130:131], 0, v[160:161]
	v_mov_b32_e32 v209, 0
	v_mov_b32_e32 v208, 0x10000
	v_lshl_add_u64 v[194:195], v[208:209], 0, v[170:171]
	v_mov_b32_e32 v208, 0x20000
	v_lshl_add_u64 v[196:197], v[208:209], 0, v[170:171]
	v_mov_b32_e32 v208, 0x30000
	v_lshl_add_u64 v[198:199], v[208:209], 0, v[170:171]
	v_mov_b32_e32 v208, 0x80000
	v_lshl_add_u64 v[200:201], v[208:209], 0, v[170:171]
	v_mov_b32_e32 v208, 0x90000
	v_lshl_add_u64 v[202:203], v[208:209], 0, v[170:171]
	v_mov_b32_e32 v208, 0xa0000
	v_lshl_add_u64 v[204:205], v[208:209], 0, v[170:171]
	v_mov_b32_e32 v208, 0xb0000
	v_lshl_add_u64 v[206:207], v[208:209], 0, v[170:171]
	global_load_dwordx4 v[130:133], v[170:171], off
	global_load_dwordx4 v[134:137], v[170:171], off offset:256
	global_load_dwordx4 v[138:141], v[194:195], off
	global_load_dwordx4 v[158:161], v[194:195], off offset:256
	global_load_dwordx4 v[162:165], v[196:197], off
	global_load_dwordx4 v[166:169], v[196:197], off offset:256
	global_load_dwordx4 v[178:181], v[198:199], off
	global_load_dwordx4 v[182:185], v[198:199], off offset:256
	s_waitcnt vmcnt(7)
	v_cvt_f32_f16_e32 v186, v130
	v_cvt_f32_f16_sdwa v187, v130 dst_sel:DWORD dst_unused:UNUSED_PAD src0_sel:WORD_1
	v_cvt_f32_f16_e32 v188, v131
	v_cvt_f32_f16_sdwa v189, v131 dst_sel:DWORD dst_unused:UNUSED_PAD src0_sel:WORD_1
	v_cvt_f32_f16_e32 v190, v132
	v_cvt_f32_f16_sdwa v191, v132 dst_sel:DWORD dst_unused:UNUSED_PAD src0_sel:WORD_1
	v_cvt_f32_f16_e32 v192, v133
	v_cvt_f32_f16_sdwa v193, v133 dst_sel:DWORD dst_unused:UNUSED_PAD src0_sel:WORD_1
	global_load_dwordx4 v[130:133], v[200:201], off
	v_pk_add_f32 v[126:127], v[186:187], v[126:127]
	v_pk_add_f32 v[128:129], v[188:189], v[128:129]
	v_pk_add_f32 v[122:123], v[190:191], v[122:123]
	v_pk_add_f32 v[124:125], v[192:193], v[124:125]
	v_cvt_pk_f16_f32 v125, v124, v125
	v_cvt_pk_f16_f32 v124, v122, v123
	v_cvt_pk_f16_f32 v123, v128, v129
	v_cvt_pk_f16_f32 v122, v126, v127
	global_store_dwordx4 v[170:171], v[122:125], off
	s_waitcnt vmcnt(8)
	v_cvt_f32_f16_e32 v186, v134
	v_cvt_f32_f16_sdwa v187, v134 dst_sel:DWORD dst_unused:UNUSED_PAD src0_sel:WORD_1
	v_cvt_f32_f16_e32 v188, v135
	v_cvt_f32_f16_sdwa v189, v135 dst_sel:DWORD dst_unused:UNUSED_PAD src0_sel:WORD_1
	v_cvt_f32_f16_e32 v190, v136
	v_cvt_f32_f16_sdwa v191, v136 dst_sel:DWORD dst_unused:UNUSED_PAD src0_sel:WORD_1
	v_cvt_f32_f16_e32 v192, v137
	v_cvt_f32_f16_sdwa v193, v137 dst_sel:DWORD dst_unused:UNUSED_PAD src0_sel:WORD_1
	global_load_dwordx4 v[134:137], v[200:201], off offset:256
	v_pk_add_f32 v[118:119], v[186:187], v[118:119]
	v_pk_add_f32 v[120:121], v[188:189], v[120:121]
	v_pk_add_f32 v[114:115], v[190:191], v[114:115]
	v_pk_add_f32 v[116:117], v[192:193], v[116:117]
	v_cvt_pk_f16_f32 v117, v116, v117
	v_cvt_pk_f16_f32 v116, v114, v115
	v_cvt_pk_f16_f32 v115, v120, v121
	v_cvt_pk_f16_f32 v114, v118, v119
	global_store_dwordx4 v[170:171], v[114:117], off offset:256
	s_waitcnt vmcnt(9)
	v_cvt_f32_f16_e32 v186, v138
	v_cvt_f32_f16_sdwa v187, v138 dst_sel:DWORD dst_unused:UNUSED_PAD src0_sel:WORD_1
	v_cvt_f32_f16_e32 v188, v139
	v_cvt_f32_f16_sdwa v189, v139 dst_sel:DWORD dst_unused:UNUSED_PAD src0_sel:WORD_1
	v_cvt_f32_f16_e32 v190, v140
	v_cvt_f32_f16_sdwa v191, v140 dst_sel:DWORD dst_unused:UNUSED_PAD src0_sel:WORD_1
	v_cvt_f32_f16_e32 v192, v141
	v_cvt_f32_f16_sdwa v193, v141 dst_sel:DWORD dst_unused:UNUSED_PAD src0_sel:WORD_1
	global_load_dwordx4 v[138:141], v[202:203], off
	v_pk_add_f32 v[110:111], v[186:187], v[110:111]
	v_pk_add_f32 v[112:113], v[188:189], v[112:113]
	v_pk_add_f32 v[106:107], v[190:191], v[106:107]
	v_pk_add_f32 v[108:109], v[192:193], v[108:109]
	v_cvt_pk_f16_f32 v109, v108, v109
	v_cvt_pk_f16_f32 v108, v106, v107
	v_cvt_pk_f16_f32 v107, v112, v113
	v_cvt_pk_f16_f32 v106, v110, v111
	global_store_dwordx4 v[194:195], v[106:109], off
	s_waitcnt vmcnt(10)
	v_cvt_f32_f16_e32 v186, v158
	v_cvt_f32_f16_sdwa v187, v158 dst_sel:DWORD dst_unused:UNUSED_PAD src0_sel:WORD_1
	v_cvt_f32_f16_e32 v188, v159
	v_cvt_f32_f16_sdwa v189, v159 dst_sel:DWORD dst_unused:UNUSED_PAD src0_sel:WORD_1
	v_cvt_f32_f16_e32 v190, v160
	v_cvt_f32_f16_sdwa v191, v160 dst_sel:DWORD dst_unused:UNUSED_PAD src0_sel:WORD_1
	v_cvt_f32_f16_e32 v192, v161
	v_cvt_f32_f16_sdwa v193, v161 dst_sel:DWORD dst_unused:UNUSED_PAD src0_sel:WORD_1
	global_load_dwordx4 v[158:161], v[202:203], off offset:256
	v_pk_add_f32 v[102:103], v[186:187], v[102:103]
	v_pk_add_f32 v[104:105], v[188:189], v[104:105]
	v_pk_add_f32 v[98:99], v[190:191], v[98:99]
	v_pk_add_f32 v[100:101], v[192:193], v[100:101]
	v_cvt_pk_f16_f32 v101, v100, v101
	v_cvt_pk_f16_f32 v100, v98, v99
	v_cvt_pk_f16_f32 v99, v104, v105
	v_cvt_pk_f16_f32 v98, v102, v103
	global_store_dwordx4 v[194:195], v[98:101], off offset:256
	s_waitcnt vmcnt(11)
	v_cvt_f32_f16_e32 v186, v162
	v_cvt_f32_f16_sdwa v187, v162 dst_sel:DWORD dst_unused:UNUSED_PAD src0_sel:WORD_1
	v_cvt_f32_f16_e32 v188, v163
	v_cvt_f32_f16_sdwa v189, v163 dst_sel:DWORD dst_unused:UNUSED_PAD src0_sel:WORD_1
	v_cvt_f32_f16_e32 v190, v164
	v_cvt_f32_f16_sdwa v191, v164 dst_sel:DWORD dst_unused:UNUSED_PAD src0_sel:WORD_1
	v_cvt_f32_f16_e32 v192, v165
	v_cvt_f32_f16_sdwa v193, v165 dst_sel:DWORD dst_unused:UNUSED_PAD src0_sel:WORD_1
	global_load_dwordx4 v[162:165], v[204:205], off
	v_pk_add_f32 v[94:95], v[186:187], v[94:95]
	v_pk_add_f32 v[96:97], v[188:189], v[96:97]
	v_pk_add_f32 v[90:91], v[190:191], v[90:91]
	v_pk_add_f32 v[92:93], v[192:193], v[92:93]
	v_cvt_pk_f16_f32 v93, v92, v93
	v_cvt_pk_f16_f32 v92, v90, v91
	v_cvt_pk_f16_f32 v91, v96, v97
	v_cvt_pk_f16_f32 v90, v94, v95
	global_store_dwordx4 v[196:197], v[90:93], off
	s_waitcnt vmcnt(12)
	v_cvt_f32_f16_e32 v186, v166
	v_cvt_f32_f16_sdwa v187, v166 dst_sel:DWORD dst_unused:UNUSED_PAD src0_sel:WORD_1
	v_cvt_f32_f16_e32 v188, v167
	v_cvt_f32_f16_sdwa v189, v167 dst_sel:DWORD dst_unused:UNUSED_PAD src0_sel:WORD_1
	v_cvt_f32_f16_e32 v190, v168
	v_cvt_f32_f16_sdwa v191, v168 dst_sel:DWORD dst_unused:UNUSED_PAD src0_sel:WORD_1
	v_cvt_f32_f16_e32 v192, v169
	v_cvt_f32_f16_sdwa v193, v169 dst_sel:DWORD dst_unused:UNUSED_PAD src0_sel:WORD_1
	global_load_dwordx4 v[166:169], v[204:205], off offset:256
	v_pk_add_f32 v[86:87], v[186:187], v[86:87]
	v_pk_add_f32 v[88:89], v[188:189], v[88:89]
	v_pk_add_f32 v[82:83], v[190:191], v[82:83]
	v_pk_add_f32 v[84:85], v[192:193], v[84:85]
	v_cvt_pk_f16_f32 v85, v84, v85
	v_cvt_pk_f16_f32 v84, v82, v83
	v_cvt_pk_f16_f32 v83, v88, v89
	v_cvt_pk_f16_f32 v82, v86, v87
	global_store_dwordx4 v[196:197], v[82:85], off offset:256
	s_waitcnt vmcnt(13)
	v_cvt_f32_f16_e32 v186, v178
	v_cvt_f32_f16_sdwa v187, v178 dst_sel:DWORD dst_unused:UNUSED_PAD src0_sel:WORD_1
	v_cvt_f32_f16_e32 v188, v179
	v_cvt_f32_f16_sdwa v189, v179 dst_sel:DWORD dst_unused:UNUSED_PAD src0_sel:WORD_1
	v_cvt_f32_f16_e32 v190, v180
	v_cvt_f32_f16_sdwa v191, v180 dst_sel:DWORD dst_unused:UNUSED_PAD src0_sel:WORD_1
	v_cvt_f32_f16_e32 v192, v181
	v_cvt_f32_f16_sdwa v193, v181 dst_sel:DWORD dst_unused:UNUSED_PAD src0_sel:WORD_1
	global_load_dwordx4 v[178:181], v[206:207], off
	v_pk_add_f32 v[78:79], v[186:187], v[78:79]
	v_pk_add_f32 v[80:81], v[188:189], v[80:81]
	v_pk_add_f32 v[74:75], v[190:191], v[74:75]
	v_pk_add_f32 v[76:77], v[192:193], v[76:77]
	v_cvt_pk_f16_f32 v77, v76, v77
	v_cvt_pk_f16_f32 v76, v74, v75
	v_cvt_pk_f16_f32 v75, v80, v81
	v_cvt_pk_f16_f32 v74, v78, v79
	global_store_dwordx4 v[198:199], v[74:77], off
	s_waitcnt vmcnt(14)
	v_cvt_f32_f16_e32 v186, v182
	v_cvt_f32_f16_sdwa v187, v182 dst_sel:DWORD dst_unused:UNUSED_PAD src0_sel:WORD_1
	v_cvt_f32_f16_e32 v188, v183
	v_cvt_f32_f16_sdwa v189, v183 dst_sel:DWORD dst_unused:UNUSED_PAD src0_sel:WORD_1
	v_cvt_f32_f16_e32 v190, v184
	v_cvt_f32_f16_sdwa v191, v184 dst_sel:DWORD dst_unused:UNUSED_PAD src0_sel:WORD_1
	v_cvt_f32_f16_e32 v192, v185
	v_cvt_f32_f16_sdwa v193, v185 dst_sel:DWORD dst_unused:UNUSED_PAD src0_sel:WORD_1
	global_load_dwordx4 v[182:185], v[206:207], off offset:256
	v_pk_add_f32 v[70:71], v[186:187], v[70:71]
	v_pk_add_f32 v[72:73], v[188:189], v[72:73]
	v_pk_add_f32 v[66:67], v[190:191], v[66:67]
	v_pk_add_f32 v[68:69], v[192:193], v[68:69]
	v_cvt_pk_f16_f32 v69, v68, v69
	v_cvt_pk_f16_f32 v68, v66, v67
	v_cvt_pk_f16_f32 v67, v72, v73
	v_cvt_pk_f16_f32 v66, v70, v71
	global_store_dwordx4 v[198:199], v[66:69], off offset:256
	s_waitcnt vmcnt(15)
	v_cvt_f32_f16_e32 v186, v130
	v_cvt_f32_f16_sdwa v187, v130 dst_sel:DWORD dst_unused:UNUSED_PAD src0_sel:WORD_1
	v_cvt_f32_f16_e32 v188, v131
	v_cvt_f32_f16_sdwa v189, v131 dst_sel:DWORD dst_unused:UNUSED_PAD src0_sel:WORD_1
	v_cvt_f32_f16_e32 v190, v132
	v_cvt_f32_f16_sdwa v191, v132 dst_sel:DWORD dst_unused:UNUSED_PAD src0_sel:WORD_1
	v_cvt_f32_f16_e32 v192, v133
	v_cvt_f32_f16_sdwa v193, v133 dst_sel:DWORD dst_unused:UNUSED_PAD src0_sel:WORD_1
	v_pk_add_f32 v[62:63], v[186:187], v[62:63]
	v_pk_add_f32 v[64:65], v[188:189], v[64:65]
	v_pk_add_f32 v[58:59], v[190:191], v[58:59]
	v_pk_add_f32 v[60:61], v[192:193], v[60:61]
	v_cvt_pk_f16_f32 v61, v60, v61
	v_cvt_pk_f16_f32 v60, v58, v59
	v_cvt_pk_f16_f32 v59, v64, v65
	v_cvt_pk_f16_f32 v58, v62, v63
	global_store_dwordx4 v[200:201], v[58:61], off
	s_waitcnt vmcnt(14)
	v_cvt_f32_f16_e32 v186, v134
	v_cvt_f32_f16_sdwa v187, v134 dst_sel:DWORD dst_unused:UNUSED_PAD src0_sel:WORD_1
	v_cvt_f32_f16_e32 v188, v135
	v_cvt_f32_f16_sdwa v189, v135 dst_sel:DWORD dst_unused:UNUSED_PAD src0_sel:WORD_1
	v_cvt_f32_f16_e32 v190, v136
	v_cvt_f32_f16_sdwa v191, v136 dst_sel:DWORD dst_unused:UNUSED_PAD src0_sel:WORD_1
	v_cvt_f32_f16_e32 v192, v137
	v_cvt_f32_f16_sdwa v193, v137 dst_sel:DWORD dst_unused:UNUSED_PAD src0_sel:WORD_1
	v_pk_add_f32 v[54:55], v[186:187], v[54:55]
	v_pk_add_f32 v[56:57], v[188:189], v[56:57]
	v_pk_add_f32 v[46:47], v[190:191], v[46:47]
	v_pk_add_f32 v[48:49], v[192:193], v[48:49]
	v_cvt_pk_f16_f32 v49, v48, v49
	v_cvt_pk_f16_f32 v48, v46, v47
	v_cvt_pk_f16_f32 v47, v56, v57
	v_cvt_pk_f16_f32 v46, v54, v55
	global_store_dwordx4 v[200:201], v[46:49], off offset:256
	s_waitcnt vmcnt(13)
	v_cvt_f32_f16_e32 v186, v138
	v_cvt_f32_f16_sdwa v187, v138 dst_sel:DWORD dst_unused:UNUSED_PAD src0_sel:WORD_1
	v_cvt_f32_f16_e32 v188, v139
	v_cvt_f32_f16_sdwa v189, v139 dst_sel:DWORD dst_unused:UNUSED_PAD src0_sel:WORD_1
	v_cvt_f32_f16_e32 v190, v140
	v_cvt_f32_f16_sdwa v191, v140 dst_sel:DWORD dst_unused:UNUSED_PAD src0_sel:WORD_1
	v_cvt_f32_f16_e32 v192, v141
	v_cvt_f32_f16_sdwa v193, v141 dst_sel:DWORD dst_unused:UNUSED_PAD src0_sel:WORD_1
	v_pk_add_f32 v[50:51], v[186:187], v[50:51]
	v_pk_add_f32 v[52:53], v[188:189], v[52:53]
	v_pk_add_f32 v[42:43], v[190:191], v[42:43]
	v_pk_add_f32 v[44:45], v[192:193], v[44:45]
	v_cvt_pk_f16_f32 v45, v44, v45
	v_cvt_pk_f16_f32 v44, v42, v43
	v_cvt_pk_f16_f32 v43, v52, v53
	v_cvt_pk_f16_f32 v42, v50, v51
	global_store_dwordx4 v[202:203], v[42:45], off
	s_waitcnt vmcnt(12)
	v_cvt_f32_f16_e32 v186, v158
	v_cvt_f32_f16_sdwa v187, v158 dst_sel:DWORD dst_unused:UNUSED_PAD src0_sel:WORD_1
	v_cvt_f32_f16_e32 v188, v159
	v_cvt_f32_f16_sdwa v189, v159 dst_sel:DWORD dst_unused:UNUSED_PAD src0_sel:WORD_1
	v_cvt_f32_f16_e32 v190, v160
	v_cvt_f32_f16_sdwa v191, v160 dst_sel:DWORD dst_unused:UNUSED_PAD src0_sel:WORD_1
	v_cvt_f32_f16_e32 v192, v161
	v_cvt_f32_f16_sdwa v193, v161 dst_sel:DWORD dst_unused:UNUSED_PAD src0_sel:WORD_1
	v_pk_add_f32 v[30:31], v[186:187], v[30:31]
	v_pk_add_f32 v[32:33], v[188:189], v[32:33]
	v_pk_add_f32 v[26:27], v[190:191], v[26:27]
	v_pk_add_f32 v[28:29], v[192:193], v[28:29]
	v_cvt_pk_f16_f32 v29, v28, v29
	v_cvt_pk_f16_f32 v28, v26, v27
	v_cvt_pk_f16_f32 v27, v32, v33
	v_cvt_pk_f16_f32 v26, v30, v31
	global_store_dwordx4 v[202:203], v[26:29], off offset:256
	s_waitcnt vmcnt(11)
	v_cvt_f32_f16_e32 v186, v162
	v_cvt_f32_f16_sdwa v187, v162 dst_sel:DWORD dst_unused:UNUSED_PAD src0_sel:WORD_1
	v_cvt_f32_f16_e32 v188, v163
	v_cvt_f32_f16_sdwa v189, v163 dst_sel:DWORD dst_unused:UNUSED_PAD src0_sel:WORD_1
	v_cvt_f32_f16_e32 v190, v164
	v_cvt_f32_f16_sdwa v191, v164 dst_sel:DWORD dst_unused:UNUSED_PAD src0_sel:WORD_1
	v_cvt_f32_f16_e32 v192, v165
	v_cvt_f32_f16_sdwa v193, v165 dst_sel:DWORD dst_unused:UNUSED_PAD src0_sel:WORD_1
	v_pk_add_f32 v[38:39], v[186:187], v[38:39]
	v_pk_add_f32 v[40:41], v[188:189], v[40:41]
	v_pk_add_f32 v[34:35], v[190:191], v[34:35]
	v_pk_add_f32 v[36:37], v[192:193], v[36:37]
	v_cvt_pk_f16_f32 v37, v36, v37
	v_cvt_pk_f16_f32 v36, v34, v35
	v_cvt_pk_f16_f32 v35, v40, v41
	v_cvt_pk_f16_f32 v34, v38, v39
	global_store_dwordx4 v[204:205], v[34:37], off
	s_waitcnt vmcnt(10)
	v_cvt_f32_f16_e32 v186, v166
	v_cvt_f32_f16_sdwa v187, v166 dst_sel:DWORD dst_unused:UNUSED_PAD src0_sel:WORD_1
	v_cvt_f32_f16_e32 v188, v167
	v_cvt_f32_f16_sdwa v189, v167 dst_sel:DWORD dst_unused:UNUSED_PAD src0_sel:WORD_1
	v_cvt_f32_f16_e32 v190, v168
	v_cvt_f32_f16_sdwa v191, v168 dst_sel:DWORD dst_unused:UNUSED_PAD src0_sel:WORD_1
	v_cvt_f32_f16_e32 v192, v169
	v_cvt_f32_f16_sdwa v193, v169 dst_sel:DWORD dst_unused:UNUSED_PAD src0_sel:WORD_1
	v_pk_add_f32 v[22:23], v[186:187], v[22:23]
	v_pk_add_f32 v[24:25], v[188:189], v[24:25]
	v_pk_add_f32 v[18:19], v[190:191], v[18:19]
	v_pk_add_f32 v[20:21], v[192:193], v[20:21]
	v_cvt_pk_f16_f32 v21, v20, v21
	v_cvt_pk_f16_f32 v20, v18, v19
	v_cvt_pk_f16_f32 v19, v24, v25
	v_cvt_pk_f16_f32 v18, v22, v23
	global_store_dwordx4 v[204:205], v[18:21], off offset:256
	s_waitcnt vmcnt(9)
	v_cvt_f32_f16_e32 v186, v178
	v_cvt_f32_f16_sdwa v187, v178 dst_sel:DWORD dst_unused:UNUSED_PAD src0_sel:WORD_1
	v_cvt_f32_f16_e32 v188, v179
	v_cvt_f32_f16_sdwa v189, v179 dst_sel:DWORD dst_unused:UNUSED_PAD src0_sel:WORD_1
	v_cvt_f32_f16_e32 v190, v180
	v_cvt_f32_f16_sdwa v191, v180 dst_sel:DWORD dst_unused:UNUSED_PAD src0_sel:WORD_1
	v_cvt_f32_f16_e32 v192, v181
	v_cvt_f32_f16_sdwa v193, v181 dst_sel:DWORD dst_unused:UNUSED_PAD src0_sel:WORD_1
	v_pk_add_f32 v[14:15], v[186:187], v[14:15]
	v_pk_add_f32 v[16:17], v[188:189], v[16:17]
	v_pk_add_f32 v[10:11], v[190:191], v[10:11]
	v_pk_add_f32 v[12:13], v[192:193], v[12:13]
	v_cvt_pk_f16_f32 v13, v12, v13
	v_cvt_pk_f16_f32 v12, v10, v11
	v_cvt_pk_f16_f32 v11, v16, v17
	v_cvt_pk_f16_f32 v10, v14, v15
	global_store_dwordx4 v[206:207], v[10:13], off
	s_waitcnt vmcnt(8)
	v_cvt_f32_f16_e32 v186, v182
	v_cvt_f32_f16_sdwa v187, v182 dst_sel:DWORD dst_unused:UNUSED_PAD src0_sel:WORD_1
	v_cvt_f32_f16_e32 v188, v183
	v_cvt_f32_f16_sdwa v189, v183 dst_sel:DWORD dst_unused:UNUSED_PAD src0_sel:WORD_1
	v_cvt_f32_f16_e32 v190, v184
	v_cvt_f32_f16_sdwa v191, v184 dst_sel:DWORD dst_unused:UNUSED_PAD src0_sel:WORD_1
	v_cvt_f32_f16_e32 v192, v185
	v_cvt_f32_f16_sdwa v193, v185 dst_sel:DWORD dst_unused:UNUSED_PAD src0_sel:WORD_1
	v_pk_add_f32 v[6:7], v[186:187], v[6:7]
	v_pk_add_f32 v[8:9], v[188:189], v[8:9]
	v_pk_add_f32 v[2:3], v[190:191], v[2:3]
	v_pk_add_f32 v[4:5], v[192:193], v[4:5]
	v_cvt_pk_f16_f32 v5, v4, v5
	v_cvt_pk_f16_f32 v4, v2, v3
	v_cvt_pk_f16_f32 v3, v8, v9
	v_cvt_pk_f16_f32 v2, v6, v7
	global_store_dwordx4 v[206:207], v[2:5], off offset:256
	s_mov_b64 s[0:1], -1
	s_andn2_b64 vcc, exec, s[2:3]
	s_cbranch_vccnz .LBB0_3698
	s_andn2_b64 vcc, exec, s[8:9]
	s_cbranch_vccnz .LBB0_3697
	s_barrier
	s_branch .LBB0_3697
